# v5 + GEMM loops: s_nop after each M0 write replaced by one of the segment's ds_read_b128 (moved later)
# speedup vs baseline: 1.0061x; 1.0061x over previous
; #define PG8_STAGE(bufoff, gbase, voff) do { _Pragma("unroll") for (int _i = 0; _i < 2; ++_i) \
;         { unsigned vo_ = (voff) + _i * voff##_d; asm volatile("" : "+v"(vo_)); __builtin_amdgcn_global_load_lds((const unsigned*)((const char*)(gbase) + vo_), (PG8_LAS unsigned*)(lds + (bufoff) + ldsw + _i * 8192), 16, 0, 0); } } while (0)
; #define PG8_LDA(dst, b, h) do { _Pragma("unroll") for (int m = 0; m < 4; ++m) _Pragma("unroll") for (int k = 0; k < 2; ++k) dst[m][k] = *(const PG8_LAS bf16x8*)(lds + PG8_SA(b, h) + aoff + m * 2048 + k * 1024); } while (0)
; #define PG8_LDB(dst, b, h) do { _Pragma("unroll") for (int n = 0; n < 2; ++n) _Pragma("unroll") for (int k = 0; k < 2; ++k) dst[n][k] = *(const PG8_LAS bf16x8*)(lds + PG8_SB(b, h) + boff + n * 2048 + k * 1024); } while (0)
; #define PG8_WAIT_V(n) asm volatile("s_waitcnt vmcnt(" #n ")" ::: "memory")
; #define PG8_WAIT_L(n) asm volatile("s_waitcnt lgkmcnt(" #n ")" ::: "memory")
; #define PG8_BAR __builtin_amdgcn_s_barrier()
; #define PG8_SCHED __builtin_amdgcn_sched_barrier(0)
; template <class Epi, class Sched, bool ALIGN_EPI, bool F8 = false>
; __device__ __forceinline__ void gemm_phase(PG8_LAS unsigned char* lds, const Gemm g, const Sched& S, const Epi& E, const int wid) {
;     ...
;             PG8_LDB(B0, 0, 0); PG8_LDB(B1, 0, 1); PG8_SCHED; PG8_LDA(At, 0, 0); PG8_STAGE(PG8_SA(1, 1), a1 + hA, voffA);
;             PG8_WAIT_V(8); PG8_WAIT_L(0); PG8_BAR; PG8_MMA(0, 0, At, B0); PG8_MMA(0, 1, At, B1); PG8_BAR; PG8_SCHED;
;             PG8_LDA(At, 0, 1); PG8_STAGE(PG8_SB(0, 0), b2, voffB); PG8_STAGE(PG8_SB(0, 1), b2 + hB, voffB); PG8_STAGE(PG8_SA(0, 0), a2, voffA);
;             PG8_WAIT_V(8); PG8_WAIT_L(0); PG8_BAR; PG8_MMA(1, 0, At, B0); PG8_MMA(1, 1, At, B1); PG8_BAR; PG8_SCHED;
.LBB0_140:
	s_add_i32 s57, s28, 2
	s_add_u32 s30, s26, 0xfffc0080
	s_addc_u32 s29, s27, -1
	s_add_i32 s58, 0, 0x10000
	s_cmp_eq_u32 s49, s28
	s_cselect_b32 s29, s13, s29
	s_cselect_b32 s28, s15, s30
	s_cselect_b32 s31, s53, s56
	s_cselect_b32 s30, s54, s55
	s_add_i32 s60, 0, 0x14000
	v_add_u32_e32 v146, s58, v132
	v_add_u32_e32 v162, s60, v132
	ds_read_b128 v[134:137], v146
	ds_read_b128 v[138:141], v146 offset:1024
	ds_read_b128 v[142:145], v146 offset:2048
	ds_read_b128 v[146:149], v146 offset:3072
	ds_read_b128 v[150:153], v162
	ds_read_b128 v[154:157], v162 offset:1024
	ds_read_b128 v[158:161], v162 offset:2048
	ds_read_b128 v[162:165], v162 offset:3072
	ds_read_b128 v[166:169], v133
	ds_read_b128 v[170:173], v133 offset:1024
	ds_read_b128 v[174:177], v133 offset:2048
	ds_read_b128 v[178:181], v133 offset:3072
	ds_read_b128 v[182:185], v133 offset:4096
	ds_read_b128 v[186:189], v133 offset:5120
	s_add_i32 m0, s25, 0xc000
	ds_read_b128 v[190:193], v133 offset:6144
	global_load_lds_dwordx4 v128, s[26:27]
	s_add_i32 m0, s25, 0xe000
	ds_read_b128 v[194:197], v133 offset:7168
	global_load_lds_dwordx4 v131, s[26:27]
	s_waitcnt vmcnt(8)
	s_waitcnt lgkmcnt(0)
	s_barrier
	s_setprio 1
	s_waitcnt lgkmcnt(0)
	v_mfma_f32_16x16x128_f8f6f4 v[124:127], v[134:141], v[166:173], v[124:127]
	v_mfma_f32_16x16x128_f8f6f4 v[120:123], v[142:149], v[166:173], v[120:123]
	v_mfma_f32_16x16x128_f8f6f4 v[108:111], v[134:141], v[174:181], v[108:111]
	v_mfma_f32_16x16x128_f8f6f4 v[104:107], v[142:149], v[174:181], v[104:107]
	v_mfma_f32_16x16x128_f8f6f4 v[206:209], v[134:141], v[182:189], v[92:95]
	v_mfma_f32_16x16x128_f8f6f4 v[210:213], v[142:149], v[182:189], v[88:91]
	v_mfma_f32_16x16x128_f8f6f4 v[214:217], v[134:141], v[190:197], v[76:79]
	v_mfma_f32_16x16x128_f8f6f4 v[218:221], v[142:149], v[190:197], v[72:75]
	s_setprio 0
	s_setprio 1
	v_mfma_f32_16x16x128_f8f6f4 v[116:119], v[150:157], v[166:173], v[116:119]
	v_mfma_f32_16x16x128_f8f6f4 v[112:115], v[158:165], v[166:173], v[112:115]
	v_mfma_f32_16x16x128_f8f6f4 v[100:103], v[150:157], v[174:181], v[100:103]
	v_mfma_f32_16x16x128_f8f6f4 v[96:99], v[158:165], v[174:181], v[96:99]
	v_mfma_f32_16x16x128_f8f6f4 v[166:169], v[150:157], v[182:189], v[84:87]
	v_mfma_f32_16x16x128_f8f6f4 v[170:173], v[158:165], v[182:189], v[80:83]
	v_mfma_f32_16x16x128_f8f6f4 v[174:177], v[150:157], v[190:197], v[68:71]
	v_mfma_f32_16x16x128_f8f6f4 v[178:181], v[158:165], v[190:197], v[64:67]
	s_setprio 0
	s_barrier
	s_add_i32 s58, s58, s39
	s_nop 2
	ds_read_b128 v[64:67], v133 offset:16384
	ds_read_b128 v[68:71], v133 offset:17408
	ds_read_b128 v[72:75], v133 offset:18432
	s_mov_b32 m0, s58
	ds_read_b128 v[76:79], v133 offset:19456
	global_load_lds_dwordx4 v129, s[30:31]
	s_add_i32 m0, s58, 0x2000
	s_add_u32 s58, s30, 0x40000
	global_load_lds_dwordx4 v130, s[30:31]
	s_addc_u32 s59, s31, 0
	s_add_i32 s60, s60, s39
	s_mov_b32 m0, s60
	ds_read_b128 v[80:83], v133 offset:20480
	global_load_lds_dwordx4 v129, s[58:59]
	s_add_i32 m0, s60, 0x2000
	ds_read_b128 v[84:87], v133 offset:21504
	global_load_lds_dwordx4 v130, s[58:59]
	s_mov_b32 m0, s25
	ds_read_b128 v[88:91], v133 offset:22528
	global_load_lds_dwordx4 v128, s[28:29]
	s_mov_b32 m0, s41
	ds_read_b128 v[92:95], v133 offset:23552
	global_load_lds_dwordx4 v131, s[28:29]
	s_waitcnt vmcnt(8)
	s_waitcnt lgkmcnt(0)
	s_barrier
	s_setprio 1
	s_waitcnt lgkmcnt(0)
	v_mfma_f32_16x16x128_f8f6f4 v[60:63], v[134:141], v[64:71], v[60:63]
	v_mfma_f32_16x16x128_f8f6f4 v[56:59], v[142:149], v[64:71], v[56:59]
	v_mfma_f32_16x16x128_f8f6f4 v[182:185], v[134:141], v[72:79], v[44:47]
	v_mfma_f32_16x16x128_f8f6f4 v[186:189], v[142:149], v[72:79], v[40:43]
	v_mfma_f32_16x16x128_f8f6f4 v[190:193], v[134:141], v[80:87], v[28:31]
	v_mfma_f32_16x16x128_f8f6f4 v[194:197], v[142:149], v[80:87], v[24:27]
	v_mfma_f32_16x16x128_f8f6f4 v[242:245], v[134:141], v[88:95], v[12:15]
	v_mfma_f32_16x16x128_f8f6f4 v[246:249], v[142:149], v[88:95], v[8:11]
	s_setprio 0
	s_setprio 1
	v_mfma_f32_16x16x128_f8f6f4 v[52:55], v[150:157], v[64:71], v[52:55]
	v_mfma_f32_16x16x128_f8f6f4 v[48:51], v[158:165], v[64:71], v[48:51]
	v_mfma_f32_16x16x128_f8f6f4 v[250:253], v[150:157], v[72:79], v[36:39]
	v_mfma_f32_16x16x128_f8f6f4 v[228:231], v[158:165], v[72:79], v[32:35]
	v_mfma_f32_16x16x128_f8f6f4 v[202:205], v[150:157], v[80:87], v[20:23]
	v_mfma_f32_16x16x128_f8f6f4 v[236:239], v[158:165], v[80:87], v[16:19]
	v_mfma_f32_16x16x128_f8f6f4 v[224:227], v[150:157], v[88:95], v[4:7]
	v_mfma_f32_16x16x128_f8f6f4 v[232:235], v[158:165], v[88:95], v[0:3]
	s_setprio 0
	s_barrier
; #define PG8_STAGE(bufoff, gbase, voff) do { _Pragma("unroll") for (int _i = 0; _i < 2; ++_i) \
;         { unsigned vo_ = (voff) + _i * voff##_d; asm volatile("" : "+v"(vo_)); __builtin_amdgcn_global_load_lds((const unsigned*)((const char*)(gbase) + vo_), (PG8_LAS unsigned*)(lds + (bufoff) + ldsw + _i * 8192), 16, 0, 0); } } while (0)
; #define PG8_LDA(dst, b, h) do { _Pragma("unroll") for (int m = 0; m < 4; ++m) _Pragma("unroll") for (int k = 0; k < 2; ++k) dst[m][k] = *(const PG8_LAS bf16x8*)(lds + PG8_SA(b, h) + aoff + m * 2048 + k * 1024); } while (0)
; #define PG8_LDB(dst, b, h) do { _Pragma("unroll") for (int n = 0; n < 2; ++n) _Pragma("unroll") for (int k = 0; k < 2; ++k) dst[n][k] = *(const PG8_LAS bf16x8*)(lds + PG8_SB(b, h) + boff + n * 2048 + k * 1024); } while (0)
; #define PG8_WAIT_V(n) asm volatile("s_waitcnt vmcnt(" #n ")" ::: "memory")
; #define PG8_WAIT_L(n) asm volatile("s_waitcnt lgkmcnt(" #n ")" ::: "memory")
; #define PG8_BAR __builtin_amdgcn_s_barrier()
; #define PG8_SCHED __builtin_amdgcn_sched_barrier(0)
; template <class Epi, class Sched, bool ALIGN_EPI, bool F8 = false>
; __device__ __forceinline__ void gemm_phase(PG8_LAS unsigned char* lds, const Gemm g, const Sched& S, const Epi& E, const int wid) {
;     ...
;             PG8_LDB(B0, 1, 0); PG8_LDB(B1, 1, 1); PG8_SCHED; PG8_LDA(At, 1, 0); PG8_STAGE(PG8_SA(0, 1), a2 + hA, voffA);
;             PG8_WAIT_V(8); PG8_WAIT_L(0); PG8_BAR; PG8_MMA(0, 0, At, B0); PG8_MMA(0, 1, At, B1); PG8_BAR; PG8_SCHED;
;             PG8_LDA(At, 1, 1); PG8_STAGE(PG8_SB(1, 0), b3, voffB); PG8_STAGE(PG8_SB(1, 1), b3 + hB, voffB); PG8_STAGE(PG8_SA(1, 0), a3, voffA);
;             PG8_WAIT_V(8); PG8_WAIT_L(0); PG8_BAR; PG8_MMA(1, 0, At, B0); PG8_MMA(1, 1, At, B1); PG8_BAR; PG8_SCHED;
	s_add_i32 s60, 0, 0x18000
	v_add_u32_e32 v8, s60, v132
	s_add_i32 s61, 0, 0x1c000
	s_nop 1
	ds_read_b128 v[0:3], v8
	ds_read_b128 v[4:7], v8 offset:1024
	ds_read_b128 v[16:19], v8 offset:2048
	ds_read_b128 v[20:23], v8 offset:3072
	v_add_u32_e32 v8, s61, v132
	ds_read_b128 v[134:137], v8
	ds_read_b128 v[138:141], v8 offset:1024
	ds_read_b128 v[142:145], v8 offset:2048
	ds_read_b128 v[146:149], v8 offset:3072
	s_add_u32 s58, s28, 0x40000
	s_mov_b32 m0, s42
	ds_read_b128 v[8:11], v133 offset:32768
	ds_read_b128 v[12:15], v133 offset:33792
	ds_read_b128 v[24:27], v133 offset:34816
	ds_read_b128 v[28:31], v133 offset:35840
	ds_read_b128 v[32:35], v133 offset:36864
	ds_read_b128 v[36:39], v133 offset:37888
	s_addc_u32 s59, s29, 0
	ds_read_b128 v[40:43], v133 offset:38912
	global_load_lds_dwordx4 v128, s[58:59]
	s_mov_b32 m0, s43
	ds_read_b128 v[44:47], v133 offset:39936
	global_load_lds_dwordx4 v131, s[58:59]
	s_waitcnt vmcnt(8)
	s_waitcnt lgkmcnt(0)
	s_barrier
	s_setprio 1
	s_waitcnt lgkmcnt(0)
	v_mfma_f32_16x16x128_f8f6f4 v[124:127], v[0:7], v[8:15], v[124:127]
	v_mfma_f32_16x16x128_f8f6f4 v[120:123], v[16:23], v[8:15], v[120:123]
	v_mfma_f32_16x16x128_f8f6f4 v[108:111], v[0:7], v[24:31], v[108:111]
	v_mfma_f32_16x16x128_f8f6f4 v[104:107], v[16:23], v[24:31], v[104:107]
	v_mfma_f32_16x16x128_f8f6f4 v[92:95], v[0:7], v[32:39], v[206:209]
	v_mfma_f32_16x16x128_f8f6f4 v[88:91], v[16:23], v[32:39], v[210:213]
	v_mfma_f32_16x16x128_f8f6f4 v[76:79], v[0:7], v[40:47], v[214:217]
	v_mfma_f32_16x16x128_f8f6f4 v[72:75], v[16:23], v[40:47], v[218:221]
	s_setprio 0
	s_setprio 1
	v_mfma_f32_16x16x128_f8f6f4 v[116:119], v[134:141], v[8:15], v[116:119]
	v_mfma_f32_16x16x128_f8f6f4 v[112:115], v[142:149], v[8:15], v[112:115]
	v_mfma_f32_16x16x128_f8f6f4 v[100:103], v[134:141], v[24:31], v[100:103]
	v_mfma_f32_16x16x128_f8f6f4 v[96:99], v[142:149], v[24:31], v[96:99]
	v_mfma_f32_16x16x128_f8f6f4 v[84:87], v[134:141], v[32:39], v[166:169]
	v_mfma_f32_16x16x128_f8f6f4 v[80:83], v[142:149], v[32:39], v[170:173]
	v_mfma_f32_16x16x128_f8f6f4 v[68:71], v[134:141], v[40:47], v[174:177]
	v_mfma_f32_16x16x128_f8f6f4 v[64:67], v[142:149], v[40:47], v[178:181]
	s_setprio 0
	s_barrier
	ds_read_b128 v[32:35], v133 offset:49152
	ds_read_b128 v[36:39], v133 offset:50176
	ds_read_b128 v[150:153], v133 offset:51200
	ds_read_b128 v[154:157], v133 offset:52224
	ds_read_b128 v[158:161], v133 offset:53248
	s_add_i32 s58, s60, s39
	s_add_u32 s100, s30, s2
	s_addc_u32 s101, s31, s3
	s_mov_b32 m0, s58
	ds_read_b128 v[162:165], v133 offset:54272
	global_load_lds_dwordx4 v129, s[100:101]
	s_add_i32 m0, s58, 0x2000
	s_add_u32 s100, s30, s2
	s_addc_u32 s101, s31, s3
	s_add_u32 s30, s30, 0x40080
	global_load_lds_dwordx4 v130, s[100:101]
	s_addc_u32 s31, s31, 0
	s_add_i32 s58, s61, s39
	s_mov_b32 m0, s58
	ds_read_b128 v[166:169], v133 offset:55296
	global_load_lds_dwordx4 v129, s[30:31]
	s_add_i32 m0, s58, 0x2000
	ds_read_b128 v[170:173], v133 offset:56320
	global_load_lds_dwordx4 v130, s[30:31]
	s_mov_b32 m0, s47
	s_add_u32 s100, s28, s2
	s_addc_u32 s101, s29, s3
	global_load_lds_dwordx4 v128, s[100:101]
	s_mov_b32 m0, s48
	s_add_u32 s100, s28, s2
	s_addc_u32 s101, s29, s3
	global_load_lds_dwordx4 v131, s[100:101]
	s_waitcnt vmcnt(8)
	s_waitcnt lgkmcnt(0)
	s_barrier
	s_setprio 1
	s_waitcnt lgkmcnt(0)
	v_mfma_f32_16x16x128_f8f6f4 v[60:63], v[0:7], v[32:39], v[60:63]
	v_mfma_f32_16x16x128_f8f6f4 v[56:59], v[16:23], v[32:39], v[56:59]
	v_mfma_f32_16x16x128_f8f6f4 v[44:47], v[0:7], v[150:157], v[182:185]
	v_mfma_f32_16x16x128_f8f6f4 v[40:43], v[16:23], v[150:157], v[186:189]
	v_mfma_f32_16x16x128_f8f6f4 v[28:31], v[0:7], v[158:165], v[190:193]
	v_mfma_f32_16x16x128_f8f6f4 v[24:27], v[16:23], v[158:165], v[194:197]
	v_mfma_f32_16x16x128_f8f6f4 v[12:15], v[0:7], v[166:173], v[242:245]
	v_mfma_f32_16x16x128_f8f6f4 v[8:11], v[16:23], v[166:173], v[246:249]
	s_setprio 0
	s_setprio 1
	v_mfma_f32_16x16x128_f8f6f4 v[52:55], v[134:141], v[32:39], v[52:55]
	v_mfma_f32_16x16x128_f8f6f4 v[48:51], v[142:149], v[32:39], v[48:51]
	v_mfma_f32_16x16x128_f8f6f4 v[36:39], v[134:141], v[150:157], v[250:253]
	v_mfma_f32_16x16x128_f8f6f4 v[32:35], v[142:149], v[150:157], v[228:231]
	v_mfma_f32_16x16x128_f8f6f4 v[20:23], v[134:141], v[158:165], v[202:205]
	v_mfma_f32_16x16x128_f8f6f4 v[16:19], v[142:149], v[158:165], v[236:239]
	v_mfma_f32_16x16x128_f8f6f4 v[4:7], v[134:141], v[166:173], v[224:227]
	v_mfma_f32_16x16x128_f8f6f4 v[0:3], v[142:149], v[166:173], v[232:235]
	s_setprio 0
	s_barrier
	s_add_u32 s26, s26, 0x100
	s_addc_u32 s27, s27, 0
	s_add_u32 s55, s55, 0x100
	s_addc_u32 s56, s56, 0
	s_cmp_ge_i32 s57, s44
	s_mov_b32 s28, s57
	s_cbranch_scc0 .LBB0_140
	v_mov_b32_e32 v232, v199
	v_mov_b32_e32 v233, v223
	v_mov_b32_e32 v223, 0x260
	v_mov_b32_e32 v234, 0x1e000
	v_mov_b32_e32 v235, 0x7f800000
	v_mov_b32_e32 v236, 0x7fc00000
	v_mov_b32_e32 v237, 0x7fffff
	v_mov_b64_e32 v[238:239], 0x140
	v_mov_b64_e32 v[252:253], 0x13f

; #define PG8_STAGE(bufoff, gbase, voff) do { _Pragma("unroll") for (int _i = 0; _i < 2; ++_i) \
;         { unsigned vo_ = (voff) + _i * voff##_d; asm volatile("" : "+v"(vo_)); __builtin_amdgcn_global_load_lds((const unsigned*)((const char*)(gbase) + vo_), (PG8_LAS unsigned*)(lds + (bufoff) + ldsw + _i * 8192), 16, 0, 0); } } while (0)
; #define PG8_LDA(dst, b, h) do { _Pragma("unroll") for (int m = 0; m < 4; ++m) _Pragma("unroll") for (int k = 0; k < 2; ++k) dst[m][k] = *(const PG8_LAS bf16x8*)(lds + PG8_SA(b, h) + aoff + m * 2048 + k * 1024); } while (0)
; #define PG8_LDB(dst, b, h) do { _Pragma("unroll") for (int n = 0; n < 2; ++n) _Pragma("unroll") for (int k = 0; k < 2; ++k) dst[n][k] = *(const PG8_LAS bf16x8*)(lds + PG8_SB(b, h) + boff + n * 2048 + k * 1024); } while (0)
; #define PG8_WAIT_V(n) asm volatile("s_waitcnt vmcnt(" #n ")" ::: "memory")
; #define PG8_WAIT_L(n) asm volatile("s_waitcnt lgkmcnt(" #n ")" ::: "memory")
; #define PG8_BAR __builtin_amdgcn_s_barrier()
; #define PG8_SCHED __builtin_amdgcn_sched_barrier(0)
; template <class Epi, class Sched, bool ALIGN_EPI, bool F8 = false>
; __device__ __forceinline__ void gemm_phase(PG8_LAS unsigned char* lds, const Gemm g, const Sched& S, const Epi& E, const int wid) {
;     ...
;             PG8_LDB(B0, 0, 0); PG8_LDB(B1, 0, 1); PG8_SCHED; PG8_LDA(At, 0, 0); PG8_STAGE(PG8_SA(1, 1), a1 + hA, voffA);
;             PG8_WAIT_V(8); PG8_WAIT_L(0); PG8_BAR; PG8_MMA(0, 0, At, B0); PG8_MMA(0, 1, At, B1); PG8_BAR; PG8_SCHED;
;             PG8_LDA(At, 0, 1); PG8_STAGE(PG8_SB(0, 0), b2, voffB); PG8_STAGE(PG8_SB(0, 1), b2 + hB, voffB); PG8_STAGE(PG8_SA(0, 0), a2, voffA);
;             PG8_WAIT_V(8); PG8_WAIT_L(0); PG8_BAR; PG8_MMA(1, 0, At, B0); PG8_MMA(1, 1, At, B1); PG8_BAR; PG8_SCHED;
.LBB0_160:
	s_add_i32 s59, s10, 2
	s_add_u32 s8, s6, 0xfff80080
	s_addc_u32 s9, s7, -1
	s_add_i32 s61, 0, 0x10000
	s_cmp_eq_u32 s89, s10
	s_cselect_b32 s9, s1, s9
	s_cselect_b32 s8, s12, s8
	s_cselect_b32 s11, s13, s33
	s_cselect_b32 s10, s14, s15
	s_add_i32 s94, 0, 0x14000
	v_add_u32_e32 v140, s61, v219
	v_add_u32_e32 v156, s94, v219
	ds_read_b128 v[128:131], v140
	ds_read_b128 v[132:135], v140 offset:1024
	ds_read_b128 v[136:139], v140 offset:2048
	ds_read_b128 v[140:143], v140 offset:3072
	ds_read_b128 v[144:147], v156
	ds_read_b128 v[148:151], v156 offset:1024
	ds_read_b128 v[152:155], v156 offset:2048
	ds_read_b128 v[156:159], v156 offset:3072
	ds_read_b128 v[160:163], v220
	ds_read_b128 v[164:167], v220 offset:1024
	ds_read_b128 v[168:171], v220 offset:2048
	ds_read_b128 v[172:175], v220 offset:3072
	ds_read_b128 v[176:179], v220 offset:4096
	ds_read_b128 v[180:183], v220 offset:5120
	s_add_i32 m0, s80, 0xc000
	ds_read_b128 v[184:187], v220 offset:6144
	global_load_lds_dwordx4 v217, s[6:7]
	s_add_i32 m0, s80, 0xe000
	ds_read_b128 v[188:191], v220 offset:7168
	global_load_lds_dwordx4 v218, s[6:7]
	s_waitcnt vmcnt(8)
	s_waitcnt lgkmcnt(0)
	s_barrier
	s_setprio 1
	s_waitcnt lgkmcnt(0)
	v_mfma_f32_16x16x32_bf16 v[124:127], v[128:131], v[160:163], v[124:127]
	v_mfma_f32_16x16x32_bf16 v[116:119], v[136:139], v[160:163], v[116:119]
	v_mfma_f32_16x16x32_bf16 v[108:111], v[128:131], v[168:171], v[108:111]
	v_mfma_f32_16x16x32_bf16 v[104:107], v[136:139], v[168:171], v[104:107]
	v_mfma_f32_16x16x32_bf16 v[92:95], v[128:131], v[176:179], v[92:95]
	v_mfma_f32_16x16x32_bf16 v[88:91], v[136:139], v[176:179], v[88:91]
	v_mfma_f32_16x16x32_bf16 v[76:79], v[128:131], v[184:187], v[76:79]
	v_mfma_f32_16x16x32_bf16 v[72:75], v[136:139], v[184:187], v[72:75]
	v_mfma_f32_16x16x32_bf16 v[124:127], v[132:135], v[164:167], v[124:127]
	v_mfma_f32_16x16x32_bf16 v[116:119], v[140:143], v[164:167], v[116:119]
	v_mfma_f32_16x16x32_bf16 v[108:111], v[132:135], v[172:175], v[108:111]
	v_mfma_f32_16x16x32_bf16 v[104:107], v[140:143], v[172:175], v[104:107]
	v_mfma_f32_16x16x32_bf16 v[92:95], v[132:135], v[180:183], v[92:95]
	v_mfma_f32_16x16x32_bf16 v[88:91], v[140:143], v[180:183], v[88:91]
	v_mfma_f32_16x16x32_bf16 v[76:79], v[132:135], v[188:191], v[76:79]
	v_mfma_f32_16x16x32_bf16 v[72:75], v[140:143], v[188:191], v[72:75]
	s_setprio 0
	s_setprio 1
	v_mfma_f32_16x16x32_bf16 v[120:123], v[144:147], v[160:163], v[120:123]
	v_mfma_f32_16x16x32_bf16 v[112:115], v[152:155], v[160:163], v[112:115]
	v_mfma_f32_16x16x32_bf16 v[100:103], v[144:147], v[168:171], v[100:103]
	v_mfma_f32_16x16x32_bf16 v[96:99], v[152:155], v[168:171], v[96:99]
	v_mfma_f32_16x16x32_bf16 v[84:87], v[144:147], v[176:179], v[84:87]
	v_mfma_f32_16x16x32_bf16 v[80:83], v[152:155], v[176:179], v[80:83]
	v_mfma_f32_16x16x32_bf16 v[68:71], v[144:147], v[184:187], v[68:71]
	v_mfma_f32_16x16x32_bf16 v[64:67], v[152:155], v[184:187], v[64:67]
	v_mfma_f32_16x16x32_bf16 v[120:123], v[148:151], v[164:167], v[120:123]
	v_mfma_f32_16x16x32_bf16 v[112:115], v[156:159], v[164:167], v[112:115]
	v_mfma_f32_16x16x32_bf16 v[100:103], v[148:151], v[172:175], v[100:103]
	v_mfma_f32_16x16x32_bf16 v[96:99], v[156:159], v[172:175], v[96:99]
	v_mfma_f32_16x16x32_bf16 v[84:87], v[148:151], v[180:183], v[84:87]
	v_mfma_f32_16x16x32_bf16 v[80:83], v[156:159], v[180:183], v[80:83]
	v_mfma_f32_16x16x32_bf16 v[68:71], v[148:151], v[188:191], v[68:71]
	v_mfma_f32_16x16x32_bf16 v[64:67], v[156:159], v[188:191], v[64:67]
	s_setprio 0
	s_barrier
	s_add_i32 s61, s61, s79
	ds_read_b128 v[160:163], v220 offset:16384
	ds_read_b128 v[164:167], v220 offset:17408
	ds_read_b128 v[168:171], v220 offset:18432
	s_mov_b32 m0, s61
	ds_read_b128 v[172:175], v220 offset:19456
	global_load_lds_dwordx4 v217, s[10:11]
	s_add_i32 m0, s61, 0x2000
	s_add_u32 s70, s10, 0x80000
	global_load_lds_dwordx4 v218, s[10:11]
	s_addc_u32 s71, s11, 0
	s_add_i32 s61, s94, s79
	s_mov_b32 m0, s61
	ds_read_b128 v[176:179], v220 offset:20480
	global_load_lds_dwordx4 v217, s[70:71]
	s_add_i32 m0, s61, 0x2000
	ds_read_b128 v[180:183], v220 offset:21504
	global_load_lds_dwordx4 v218, s[70:71]
	s_mov_b32 m0, s80
	ds_read_b128 v[184:187], v220 offset:22528
	global_load_lds_dwordx4 v217, s[8:9]
	s_mov_b32 m0, s81
	ds_read_b128 v[188:191], v220 offset:23552
	global_load_lds_dwordx4 v218, s[8:9]
	s_waitcnt vmcnt(8)
	s_waitcnt lgkmcnt(0)
	s_barrier
	s_setprio 1
	s_waitcnt lgkmcnt(0)
	v_mfma_f32_16x16x32_bf16 v[60:63], v[128:131], v[160:163], v[60:63]
	v_mfma_f32_16x16x32_bf16 v[56:59], v[136:139], v[160:163], v[56:59]
	v_mfma_f32_16x16x32_bf16 v[44:47], v[128:131], v[168:171], v[44:47]
	v_mfma_f32_16x16x32_bf16 v[40:43], v[136:139], v[168:171], v[40:43]
	v_mfma_f32_16x16x32_bf16 v[28:31], v[128:131], v[176:179], v[28:31]
	v_mfma_f32_16x16x32_bf16 v[24:27], v[136:139], v[176:179], v[24:27]
	v_mfma_f32_16x16x32_bf16 v[12:15], v[128:131], v[184:187], v[12:15]
	v_mfma_f32_16x16x32_bf16 v[8:11], v[136:139], v[184:187], v[8:11]
	v_mfma_f32_16x16x32_bf16 v[60:63], v[132:135], v[164:167], v[60:63]
	v_mfma_f32_16x16x32_bf16 v[56:59], v[140:143], v[164:167], v[56:59]
	v_mfma_f32_16x16x32_bf16 v[44:47], v[132:135], v[172:175], v[44:47]
	v_mfma_f32_16x16x32_bf16 v[40:43], v[140:143], v[172:175], v[40:43]
	v_mfma_f32_16x16x32_bf16 v[28:31], v[132:135], v[180:183], v[28:31]
	v_mfma_f32_16x16x32_bf16 v[24:27], v[140:143], v[180:183], v[24:27]
	v_mfma_f32_16x16x32_bf16 v[12:15], v[132:135], v[188:191], v[12:15]
	v_mfma_f32_16x16x32_bf16 v[8:11], v[140:143], v[188:191], v[8:11]
	s_setprio 0
	s_setprio 1
	v_mfma_f32_16x16x32_bf16 v[52:55], v[144:147], v[160:163], v[52:55]
	v_mfma_f32_16x16x32_bf16 v[48:51], v[152:155], v[160:163], v[48:51]
	v_mfma_f32_16x16x32_bf16 v[36:39], v[144:147], v[168:171], v[36:39]
	v_mfma_f32_16x16x32_bf16 v[32:35], v[152:155], v[168:171], v[32:35]
	v_mfma_f32_16x16x32_bf16 v[20:23], v[144:147], v[176:179], v[20:23]
	v_mfma_f32_16x16x32_bf16 v[16:19], v[152:155], v[176:179], v[16:19]
	v_mfma_f32_16x16x32_bf16 v[4:7], v[144:147], v[184:187], v[4:7]
	v_mfma_f32_16x16x32_bf16 v[0:3], v[152:155], v[184:187], v[0:3]
	v_mfma_f32_16x16x32_bf16 v[52:55], v[148:151], v[164:167], v[52:55]
	v_mfma_f32_16x16x32_bf16 v[48:51], v[156:159], v[164:167], v[48:51]
	v_mfma_f32_16x16x32_bf16 v[36:39], v[148:151], v[172:175], v[36:39]
	v_mfma_f32_16x16x32_bf16 v[32:35], v[156:159], v[172:175], v[32:35]
	v_mfma_f32_16x16x32_bf16 v[20:23], v[148:151], v[180:183], v[20:23]
	v_mfma_f32_16x16x32_bf16 v[16:19], v[156:159], v[180:183], v[16:19]
	v_mfma_f32_16x16x32_bf16 v[4:7], v[148:151], v[188:191], v[4:7]
	v_mfma_f32_16x16x32_bf16 v[0:3], v[156:159], v[188:191], v[0:3]
	s_setprio 0
	s_barrier
; #define PG8_STAGE(bufoff, gbase, voff) do { _Pragma("unroll") for (int _i = 0; _i < 2; ++_i) \
;         { unsigned vo_ = (voff) + _i * voff##_d; asm volatile("" : "+v"(vo_)); __builtin_amdgcn_global_load_lds((const unsigned*)((const char*)(gbase) + vo_), (PG8_LAS unsigned*)(lds + (bufoff) + ldsw + _i * 8192), 16, 0, 0); } } while (0)
; #define PG8_LDA(dst, b, h) do { _Pragma("unroll") for (int m = 0; m < 4; ++m) _Pragma("unroll") for (int k = 0; k < 2; ++k) dst[m][k] = *(const PG8_LAS bf16x8*)(lds + PG8_SA(b, h) + aoff + m * 2048 + k * 1024); } while (0)
; #define PG8_LDB(dst, b, h) do { _Pragma("unroll") for (int n = 0; n < 2; ++n) _Pragma("unroll") for (int k = 0; k < 2; ++k) dst[n][k] = *(const PG8_LAS bf16x8*)(lds + PG8_SB(b, h) + boff + n * 2048 + k * 1024); } while (0)
; #define PG8_WAIT_V(n) asm volatile("s_waitcnt vmcnt(" #n ")" ::: "memory")
; #define PG8_WAIT_L(n) asm volatile("s_waitcnt lgkmcnt(" #n ")" ::: "memory")
; #define PG8_BAR __builtin_amdgcn_s_barrier()
; #define PG8_SCHED __builtin_amdgcn_sched_barrier(0)
; template <class Epi, class Sched, bool ALIGN_EPI, bool F8 = false>
; __device__ __forceinline__ void gemm_phase(PG8_LAS unsigned char* lds, const Gemm g, const Sched& S, const Epi& E, const int wid) {
;     ...
;             PG8_LDB(B0, 1, 0); PG8_LDB(B1, 1, 1); PG8_SCHED; PG8_LDA(At, 1, 0); PG8_STAGE(PG8_SA(0, 1), a2 + hA, voffA);
;             PG8_WAIT_V(8); PG8_WAIT_L(0); PG8_BAR; PG8_MMA(0, 0, At, B0); PG8_MMA(0, 1, At, B1); PG8_BAR; PG8_SCHED;
;             PG8_LDA(At, 1, 1); PG8_STAGE(PG8_SB(1, 0), b3, voffB); PG8_STAGE(PG8_SB(1, 1), b3 + hB, voffB); PG8_STAGE(PG8_SA(1, 0), a3, voffA);
;             PG8_WAIT_V(8); PG8_WAIT_L(0); PG8_BAR; PG8_MMA(1, 0, At, B0); PG8_MMA(1, 1, At, B1); PG8_BAR; PG8_SCHED;
	s_add_i32 s61, 0, 0x18000
	s_add_i32 s94, 0, 0x1c000
	v_add_u32_e32 v140, s61, v219
	v_add_u32_e32 v156, s94, v219
	ds_read_b128 v[128:131], v140
	ds_read_b128 v[132:135], v140 offset:1024
	ds_read_b128 v[136:139], v140 offset:2048
	ds_read_b128 v[140:143], v140 offset:3072
	ds_read_b128 v[144:147], v156
	ds_read_b128 v[148:151], v156 offset:1024
	ds_read_b128 v[152:155], v156 offset:2048
	ds_read_b128 v[156:159], v156 offset:3072
	s_add_u32 s70, s8, 0x80000
	s_mov_b32 m0, s82
	ds_read_b128 v[160:163], v220 offset:32768
	ds_read_b128 v[164:167], v220 offset:33792
	ds_read_b128 v[168:171], v220 offset:34816
	ds_read_b128 v[172:175], v220 offset:35840
	ds_read_b128 v[176:179], v220 offset:36864
	ds_read_b128 v[180:183], v220 offset:37888
	s_addc_u32 s71, s9, 0
	ds_read_b128 v[184:187], v220 offset:38912
	global_load_lds_dwordx4 v217, s[70:71]
	s_mov_b32 m0, s83
	ds_read_b128 v[188:191], v220 offset:39936
	global_load_lds_dwordx4 v218, s[70:71]
	s_waitcnt vmcnt(8)
	s_waitcnt lgkmcnt(0)
	s_barrier
	s_setprio 1
	s_waitcnt lgkmcnt(0)
	v_mfma_f32_16x16x32_bf16 v[124:127], v[128:131], v[160:163], v[124:127]
	v_mfma_f32_16x16x32_bf16 v[116:119], v[136:139], v[160:163], v[116:119]
	v_mfma_f32_16x16x32_bf16 v[108:111], v[128:131], v[168:171], v[108:111]
	v_mfma_f32_16x16x32_bf16 v[104:107], v[136:139], v[168:171], v[104:107]
	v_mfma_f32_16x16x32_bf16 v[92:95], v[128:131], v[176:179], v[92:95]
	v_mfma_f32_16x16x32_bf16 v[88:91], v[136:139], v[176:179], v[88:91]
	v_mfma_f32_16x16x32_bf16 v[76:79], v[128:131], v[184:187], v[76:79]
	v_mfma_f32_16x16x32_bf16 v[72:75], v[136:139], v[184:187], v[72:75]
	v_mfma_f32_16x16x32_bf16 v[124:127], v[132:135], v[164:167], v[124:127]
	v_mfma_f32_16x16x32_bf16 v[116:119], v[140:143], v[164:167], v[116:119]
	v_mfma_f32_16x16x32_bf16 v[108:111], v[132:135], v[172:175], v[108:111]
	v_mfma_f32_16x16x32_bf16 v[104:107], v[140:143], v[172:175], v[104:107]
	v_mfma_f32_16x16x32_bf16 v[92:95], v[132:135], v[180:183], v[92:95]
	v_mfma_f32_16x16x32_bf16 v[88:91], v[140:143], v[180:183], v[88:91]
	v_mfma_f32_16x16x32_bf16 v[76:79], v[132:135], v[188:191], v[76:79]
	v_mfma_f32_16x16x32_bf16 v[72:75], v[140:143], v[188:191], v[72:75]
	s_setprio 0
	s_setprio 1
	v_mfma_f32_16x16x32_bf16 v[120:123], v[144:147], v[160:163], v[120:123]
	v_mfma_f32_16x16x32_bf16 v[112:115], v[152:155], v[160:163], v[112:115]
	v_mfma_f32_16x16x32_bf16 v[100:103], v[144:147], v[168:171], v[100:103]
	v_mfma_f32_16x16x32_bf16 v[96:99], v[152:155], v[168:171], v[96:99]
	v_mfma_f32_16x16x32_bf16 v[84:87], v[144:147], v[176:179], v[84:87]
	v_mfma_f32_16x16x32_bf16 v[80:83], v[152:155], v[176:179], v[80:83]
	v_mfma_f32_16x16x32_bf16 v[68:71], v[144:147], v[184:187], v[68:71]
	v_mfma_f32_16x16x32_bf16 v[64:67], v[152:155], v[184:187], v[64:67]
	v_mfma_f32_16x16x32_bf16 v[120:123], v[148:151], v[164:167], v[120:123]
	v_mfma_f32_16x16x32_bf16 v[112:115], v[156:159], v[164:167], v[112:115]
	v_mfma_f32_16x16x32_bf16 v[100:103], v[148:151], v[172:175], v[100:103]
	v_mfma_f32_16x16x32_bf16 v[96:99], v[156:159], v[172:175], v[96:99]
	v_mfma_f32_16x16x32_bf16 v[84:87], v[148:151], v[180:183], v[84:87]
	v_mfma_f32_16x16x32_bf16 v[80:83], v[156:159], v[180:183], v[80:83]
	v_mfma_f32_16x16x32_bf16 v[68:71], v[148:151], v[188:191], v[68:71]
	v_mfma_f32_16x16x32_bf16 v[64:67], v[156:159], v[188:191], v[64:67]
	s_setprio 0
	s_barrier
	ds_read_b128 v[160:163], v220 offset:49152
	ds_read_b128 v[164:167], v220 offset:50176
	ds_read_b128 v[168:171], v220 offset:51200
	ds_read_b128 v[172:175], v220 offset:52224
	ds_read_b128 v[176:179], v220 offset:53248
	s_add_i32 s61, s61, s79
	s_add_u32 s100, s10, s2
	s_addc_u32 s101, s11, s3
	s_mov_b32 m0, s61
	ds_read_b128 v[180:183], v220 offset:54272
	global_load_lds_dwordx4 v217, s[100:101]
	s_add_i32 m0, s61, 0x2000
	s_add_u32 s100, s10, s2
	s_addc_u32 s101, s11, s3
	s_add_u32 s10, s10, 0x80080
	global_load_lds_dwordx4 v218, s[100:101]
	s_addc_u32 s11, s11, 0
	s_add_i32 s61, s94, s79
	s_mov_b32 m0, s61
	ds_read_b128 v[184:187], v220 offset:55296
	global_load_lds_dwordx4 v217, s[10:11]
	s_add_i32 m0, s61, 0x2000
	ds_read_b128 v[188:191], v220 offset:56320
	global_load_lds_dwordx4 v218, s[10:11]
	s_mov_b32 m0, s87
	s_add_u32 s100, s8, s2
	s_addc_u32 s101, s9, s3
	global_load_lds_dwordx4 v217, s[100:101]
	s_mov_b32 m0, s88
	s_add_u32 s100, s8, s2
	s_addc_u32 s101, s9, s3
	global_load_lds_dwordx4 v218, s[100:101]
	s_waitcnt vmcnt(8)
	s_waitcnt lgkmcnt(0)
	s_barrier
	s_setprio 1
	s_waitcnt lgkmcnt(0)
	v_mfma_f32_16x16x32_bf16 v[60:63], v[128:131], v[160:163], v[60:63]
	v_mfma_f32_16x16x32_bf16 v[56:59], v[136:139], v[160:163], v[56:59]
	v_mfma_f32_16x16x32_bf16 v[44:47], v[128:131], v[168:171], v[44:47]
	v_mfma_f32_16x16x32_bf16 v[40:43], v[136:139], v[168:171], v[40:43]
	v_mfma_f32_16x16x32_bf16 v[28:31], v[128:131], v[176:179], v[28:31]
	v_mfma_f32_16x16x32_bf16 v[24:27], v[136:139], v[176:179], v[24:27]
	v_mfma_f32_16x16x32_bf16 v[12:15], v[128:131], v[184:187], v[12:15]
	v_mfma_f32_16x16x32_bf16 v[8:11], v[136:139], v[184:187], v[8:11]
	v_mfma_f32_16x16x32_bf16 v[60:63], v[132:135], v[164:167], v[60:63]
	v_mfma_f32_16x16x32_bf16 v[56:59], v[140:143], v[164:167], v[56:59]
	v_mfma_f32_16x16x32_bf16 v[44:47], v[132:135], v[172:175], v[44:47]
	v_mfma_f32_16x16x32_bf16 v[40:43], v[140:143], v[172:175], v[40:43]
	v_mfma_f32_16x16x32_bf16 v[28:31], v[132:135], v[180:183], v[28:31]
	v_mfma_f32_16x16x32_bf16 v[24:27], v[140:143], v[180:183], v[24:27]
	v_mfma_f32_16x16x32_bf16 v[12:15], v[132:135], v[188:191], v[12:15]
	v_mfma_f32_16x16x32_bf16 v[8:11], v[140:143], v[188:191], v[8:11]
	s_setprio 0
	s_setprio 1
	v_mfma_f32_16x16x32_bf16 v[52:55], v[144:147], v[160:163], v[52:55]
	v_mfma_f32_16x16x32_bf16 v[48:51], v[152:155], v[160:163], v[48:51]
	v_mfma_f32_16x16x32_bf16 v[36:39], v[144:147], v[168:171], v[36:39]
	v_mfma_f32_16x16x32_bf16 v[32:35], v[152:155], v[168:171], v[32:35]
	v_mfma_f32_16x16x32_bf16 v[20:23], v[144:147], v[176:179], v[20:23]
	v_mfma_f32_16x16x32_bf16 v[16:19], v[152:155], v[176:179], v[16:19]
	v_mfma_f32_16x16x32_bf16 v[4:7], v[144:147], v[184:187], v[4:7]
	v_mfma_f32_16x16x32_bf16 v[0:3], v[152:155], v[184:187], v[0:3]
	v_mfma_f32_16x16x32_bf16 v[52:55], v[148:151], v[164:167], v[52:55]
	v_mfma_f32_16x16x32_bf16 v[48:51], v[156:159], v[164:167], v[48:51]
	v_mfma_f32_16x16x32_bf16 v[36:39], v[148:151], v[172:175], v[36:39]
	v_mfma_f32_16x16x32_bf16 v[32:35], v[156:159], v[172:175], v[32:35]
	v_mfma_f32_16x16x32_bf16 v[20:23], v[148:151], v[180:183], v[20:23]
	v_mfma_f32_16x16x32_bf16 v[16:19], v[156:159], v[180:183], v[16:19]
	v_mfma_f32_16x16x32_bf16 v[4:7], v[148:151], v[188:191], v[4:7]
	v_mfma_f32_16x16x32_bf16 v[0:3], v[156:159], v[188:191], v[0:3]
	s_setprio 0
	s_barrier
	s_add_u32 s6, s6, 0x100
	s_addc_u32 s7, s7, 0
	s_add_u32 s15, s15, 0x100
	s_addc_u32 s33, s33, 0
	s_cmp_ge_i32 s59, s84
	s_mov_b32 s10, s59
	s_cbranch_scc0 .LBB0_160
	s_movk_i32 s12, 0xfff
	s_movk_i32 s94, 0x90
	s_mov_b32 s71, s37
	s_and_b64 vcc, exec, s[26:27]
	s_cbranch_vccnz .LBB0_163
	s_branch .LBB0_164

; #define PG8_STAGE(bufoff, gbase, voff) do { _Pragma("unroll") for (int _i = 0; _i < 2; ++_i) \
;         { unsigned vo_ = (voff) + _i * voff##_d; asm volatile("" : "+v"(vo_)); __builtin_amdgcn_global_load_lds((const unsigned*)((const char*)(gbase) + vo_), (PG8_LAS unsigned*)(lds + (bufoff) + ldsw + _i * 8192), 16, 0, 0); } } while (0)
; #define PG8_LDA(dst, b, h) do { _Pragma("unroll") for (int m = 0; m < 4; ++m) _Pragma("unroll") for (int k = 0; k < 2; ++k) dst[m][k] = *(const PG8_LAS bf16x8*)(lds + PG8_SA(b, h) + aoff + m * 2048 + k * 1024); } while (0)
; #define PG8_LDB(dst, b, h) do { _Pragma("unroll") for (int n = 0; n < 2; ++n) _Pragma("unroll") for (int k = 0; k < 2; ++k) dst[n][k] = *(const PG8_LAS bf16x8*)(lds + PG8_SB(b, h) + boff + n * 2048 + k * 1024); } while (0)
; #define PG8_WAIT_V(n) asm volatile("s_waitcnt vmcnt(" #n ")" ::: "memory")
; #define PG8_WAIT_L(n) asm volatile("s_waitcnt lgkmcnt(" #n ")" ::: "memory")
; #define PG8_BAR __builtin_amdgcn_s_barrier()
; #define PG8_SCHED __builtin_amdgcn_sched_barrier(0)
; template <class Epi, class Sched, bool ALIGN_EPI, bool F8 = false>
; __device__ __forceinline__ void gemm_phase(PG8_LAS unsigned char* lds, const Gemm g, const Sched& S, const Epi& E, const int wid) {
;     ...
;             PG8_LDB(B0, 0, 0); PG8_LDB(B1, 0, 1); PG8_SCHED; PG8_LDA(At, 0, 0); PG8_STAGE(PG8_SA(1, 1), a1 + hA, voffA);
;             PG8_WAIT_V(8); PG8_WAIT_L(0); PG8_BAR; PG8_MMA(0, 0, At, B0); PG8_MMA(0, 1, At, B1); PG8_BAR; PG8_SCHED;
;             PG8_LDA(At, 0, 1); PG8_STAGE(PG8_SB(0, 0), b2, voffB); PG8_STAGE(PG8_SB(0, 1), b2 + hB, voffB); PG8_STAGE(PG8_SA(0, 0), a2, voffA);
;             PG8_WAIT_V(8); PG8_WAIT_L(0); PG8_BAR; PG8_MMA(1, 0, At, B0); PG8_MMA(1, 1, At, B1); PG8_BAR; PG8_SCHED;
.LBB0_1503:
	s_add_i32 s64, s34, 2
	s_add_u32 s36, s26, 0xfffc0080
	s_addc_u32 s35, s27, -1
	s_add_i32 s65, 0, 0x10000
	s_cmp_eq_u32 s54, s34
	s_cselect_b32 s35, s25, s35
	s_cselect_b32 s34, s58, s36
	s_cselect_b32 s37, s59, s63
	s_cselect_b32 s36, s60, s61
	s_add_i32 s68, 0, 0x14000
	v_add_u32_e32 v140, s65, v148
	v_add_u32_e32 v162, s68, v148
	ds_read_b128 v[120:123], v140
	ds_read_b128 v[124:127], v140 offset:1024
	ds_read_b128 v[136:139], v140 offset:2048
	ds_read_b128 v[140:143], v140 offset:3072
	ds_read_b128 v[150:153], v162
	ds_read_b128 v[154:157], v162 offset:1024
	ds_read_b128 v[158:161], v162 offset:2048
	ds_read_b128 v[162:165], v162 offset:3072
	ds_read_b128 v[166:169], v149
	ds_read_b128 v[170:173], v149 offset:1024
	ds_read_b128 v[174:177], v149 offset:2048
	ds_read_b128 v[178:181], v149 offset:3072
	ds_read_b128 v[182:185], v149 offset:4096
	ds_read_b128 v[186:189], v149 offset:5120
	s_add_i32 m0, s45, 0xc000
	ds_read_b128 v[190:193], v149 offset:6144
	global_load_lds_dwordx4 v144, s[26:27]
	s_add_i32 m0, s45, 0xe000
	ds_read_b128 v[194:197], v149 offset:7168
	global_load_lds_dwordx4 v147, s[26:27]
	s_waitcnt vmcnt(8)
	s_waitcnt lgkmcnt(0)
	s_barrier
	s_setprio 1
	s_waitcnt lgkmcnt(0)
	v_mfma_f32_16x16x32_bf16 v[128:131], v[120:123], v[166:169], v[128:131]
	v_mfma_f32_16x16x32_bf16 v[132:135], v[136:139], v[166:169], v[132:135]
	v_mfma_f32_16x16x32_bf16 v[116:119], v[120:123], v[174:177], v[116:119]
	v_mfma_f32_16x16x32_bf16 v[112:115], v[136:139], v[174:177], v[112:115]
	v_mfma_f32_16x16x32_bf16 v[108:111], v[120:123], v[182:185], v[108:111]
	v_mfma_f32_16x16x32_bf16 v[104:107], v[136:139], v[182:185], v[104:107]
	v_mfma_f32_16x16x32_bf16 v[100:103], v[120:123], v[190:193], v[100:103]
	v_mfma_f32_16x16x32_bf16 v[96:99], v[136:139], v[190:193], v[96:99]
	v_mfma_f32_16x16x32_bf16 v[128:131], v[124:127], v[170:173], v[128:131]
	v_mfma_f32_16x16x32_bf16 v[132:135], v[140:143], v[170:173], v[132:135]
	v_mfma_f32_16x16x32_bf16 v[116:119], v[124:127], v[178:181], v[116:119]
	v_mfma_f32_16x16x32_bf16 v[112:115], v[140:143], v[178:181], v[112:115]
	v_mfma_f32_16x16x32_bf16 v[108:111], v[124:127], v[186:189], v[108:111]
	v_mfma_f32_16x16x32_bf16 v[104:107], v[140:143], v[186:189], v[104:107]
	v_mfma_f32_16x16x32_bf16 v[100:103], v[124:127], v[194:197], v[100:103]
	v_mfma_f32_16x16x32_bf16 v[96:99], v[140:143], v[194:197], v[96:99]
	s_setprio 0
	s_setprio 1
	v_mfma_f32_16x16x32_bf16 v[60:63], v[150:153], v[166:169], v[60:63]
	v_mfma_f32_16x16x32_bf16 v[56:59], v[158:161], v[166:169], v[56:59]
	v_mfma_f32_16x16x32_bf16 v[52:55], v[150:153], v[174:177], v[52:55]
	v_mfma_f32_16x16x32_bf16 v[48:51], v[158:161], v[174:177], v[48:51]
	v_mfma_f32_16x16x32_bf16 v[44:47], v[150:153], v[182:185], v[44:47]
	v_mfma_f32_16x16x32_bf16 v[40:43], v[158:161], v[182:185], v[40:43]
	v_mfma_f32_16x16x32_bf16 v[36:39], v[150:153], v[190:193], v[36:39]
	v_mfma_f32_16x16x32_bf16 v[32:35], v[158:161], v[190:193], v[32:35]
	v_mfma_f32_16x16x32_bf16 v[60:63], v[154:157], v[170:173], v[60:63]
	v_mfma_f32_16x16x32_bf16 v[56:59], v[162:165], v[170:173], v[56:59]
	v_mfma_f32_16x16x32_bf16 v[52:55], v[154:157], v[178:181], v[52:55]
	v_mfma_f32_16x16x32_bf16 v[48:51], v[162:165], v[178:181], v[48:51]
	v_mfma_f32_16x16x32_bf16 v[44:47], v[154:157], v[186:189], v[44:47]
	v_mfma_f32_16x16x32_bf16 v[40:43], v[162:165], v[186:189], v[40:43]
	v_mfma_f32_16x16x32_bf16 v[36:39], v[154:157], v[194:197], v[36:39]
	v_mfma_f32_16x16x32_bf16 v[32:35], v[162:165], v[194:197], v[32:35]
	s_setprio 0
	s_barrier
	s_add_i32 s65, s65, s44
	ds_read_b128 v[166:169], v149 offset:16384
	ds_read_b128 v[170:173], v149 offset:17408
	ds_read_b128 v[174:177], v149 offset:18432
	s_mov_b32 m0, s65
	ds_read_b128 v[178:181], v149 offset:19456
	global_load_lds_dwordx4 v145, s[36:37]
	s_add_i32 m0, s65, 0x2000
	s_add_u32 s66, s36, 0x10000
	global_load_lds_dwordx4 v146, s[36:37]
	s_addc_u32 s67, s37, 0
	s_add_i32 s65, s68, s44
	s_mov_b32 m0, s65
	ds_read_b128 v[182:185], v149 offset:20480
	global_load_lds_dwordx4 v145, s[66:67]
	s_add_i32 m0, s65, 0x2000
	ds_read_b128 v[186:189], v149 offset:21504
	global_load_lds_dwordx4 v146, s[66:67]
	s_mov_b32 m0, s45
	ds_read_b128 v[190:193], v149 offset:22528
	global_load_lds_dwordx4 v144, s[34:35]
	s_mov_b32 m0, s46
	ds_read_b128 v[194:197], v149 offset:23552
	global_load_lds_dwordx4 v147, s[34:35]
	s_waitcnt vmcnt(8)
	s_waitcnt lgkmcnt(0)
	s_barrier
	s_setprio 1
	s_waitcnt lgkmcnt(0)
	v_mfma_f32_16x16x32_bf16 v[92:95], v[120:123], v[166:169], v[92:95]
	v_mfma_f32_16x16x32_bf16 v[88:91], v[136:139], v[166:169], v[88:91]
	v_mfma_f32_16x16x32_bf16 v[84:87], v[120:123], v[174:177], v[84:87]
	v_mfma_f32_16x16x32_bf16 v[80:83], v[136:139], v[174:177], v[80:83]
	v_mfma_f32_16x16x32_bf16 v[76:79], v[120:123], v[182:185], v[76:79]
	v_mfma_f32_16x16x32_bf16 v[72:75], v[136:139], v[182:185], v[72:75]
	v_mfma_f32_16x16x32_bf16 v[68:71], v[120:123], v[190:193], v[68:71]
	v_mfma_f32_16x16x32_bf16 v[64:67], v[136:139], v[190:193], v[64:67]
	v_mfma_f32_16x16x32_bf16 v[92:95], v[124:127], v[170:173], v[92:95]
	v_mfma_f32_16x16x32_bf16 v[88:91], v[140:143], v[170:173], v[88:91]
	v_mfma_f32_16x16x32_bf16 v[84:87], v[124:127], v[178:181], v[84:87]
	v_mfma_f32_16x16x32_bf16 v[80:83], v[140:143], v[178:181], v[80:83]
	v_mfma_f32_16x16x32_bf16 v[76:79], v[124:127], v[186:189], v[76:79]
	v_mfma_f32_16x16x32_bf16 v[72:75], v[140:143], v[186:189], v[72:75]
	v_mfma_f32_16x16x32_bf16 v[68:71], v[124:127], v[194:197], v[68:71]
	v_mfma_f32_16x16x32_bf16 v[64:67], v[140:143], v[194:197], v[64:67]
	s_setprio 0
	s_setprio 1
	v_mfma_f32_16x16x32_bf16 v[28:31], v[150:153], v[166:169], v[28:31]
	v_mfma_f32_16x16x32_bf16 v[24:27], v[158:161], v[166:169], v[24:27]
	v_mfma_f32_16x16x32_bf16 v[20:23], v[150:153], v[174:177], v[20:23]
	v_mfma_f32_16x16x32_bf16 v[16:19], v[158:161], v[174:177], v[16:19]
	v_mfma_f32_16x16x32_bf16 v[12:15], v[150:153], v[182:185], v[12:15]
	v_mfma_f32_16x16x32_bf16 v[8:11], v[158:161], v[182:185], v[8:11]
	v_mfma_f32_16x16x32_bf16 v[4:7], v[150:153], v[190:193], v[4:7]
	v_mfma_f32_16x16x32_bf16 v[0:3], v[158:161], v[190:193], v[0:3]
	v_mfma_f32_16x16x32_bf16 v[28:31], v[154:157], v[170:173], v[28:31]
	v_mfma_f32_16x16x32_bf16 v[24:27], v[162:165], v[170:173], v[24:27]
	v_mfma_f32_16x16x32_bf16 v[20:23], v[154:157], v[178:181], v[20:23]
	v_mfma_f32_16x16x32_bf16 v[16:19], v[162:165], v[178:181], v[16:19]
	v_mfma_f32_16x16x32_bf16 v[12:15], v[154:157], v[186:189], v[12:15]
	v_mfma_f32_16x16x32_bf16 v[8:11], v[162:165], v[186:189], v[8:11]
	v_mfma_f32_16x16x32_bf16 v[4:7], v[154:157], v[194:197], v[4:7]
	v_mfma_f32_16x16x32_bf16 v[0:3], v[162:165], v[194:197], v[0:3]
	s_setprio 0
	s_barrier
; #define PG8_STAGE(bufoff, gbase, voff) do { _Pragma("unroll") for (int _i = 0; _i < 2; ++_i) \
;         { unsigned vo_ = (voff) + _i * voff##_d; asm volatile("" : "+v"(vo_)); __builtin_amdgcn_global_load_lds((const unsigned*)((const char*)(gbase) + vo_), (PG8_LAS unsigned*)(lds + (bufoff) + ldsw + _i * 8192), 16, 0, 0); } } while (0)
; #define PG8_LDA(dst, b, h) do { _Pragma("unroll") for (int m = 0; m < 4; ++m) _Pragma("unroll") for (int k = 0; k < 2; ++k) dst[m][k] = *(const PG8_LAS bf16x8*)(lds + PG8_SA(b, h) + aoff + m * 2048 + k * 1024); } while (0)
; #define PG8_LDB(dst, b, h) do { _Pragma("unroll") for (int n = 0; n < 2; ++n) _Pragma("unroll") for (int k = 0; k < 2; ++k) dst[n][k] = *(const PG8_LAS bf16x8*)(lds + PG8_SB(b, h) + boff + n * 2048 + k * 1024); } while (0)
; #define PG8_WAIT_V(n) asm volatile("s_waitcnt vmcnt(" #n ")" ::: "memory")
; #define PG8_WAIT_L(n) asm volatile("s_waitcnt lgkmcnt(" #n ")" ::: "memory")
; #define PG8_BAR __builtin_amdgcn_s_barrier()
; #define PG8_SCHED __builtin_amdgcn_sched_barrier(0)
; template <class Epi, class Sched, bool ALIGN_EPI, bool F8 = false>
; __device__ __forceinline__ void gemm_phase(PG8_LAS unsigned char* lds, const Gemm g, const Sched& S, const Epi& E, const int wid) {
;     ...
;             PG8_LDB(B0, 1, 0); PG8_LDB(B1, 1, 1); PG8_SCHED; PG8_LDA(At, 1, 0); PG8_STAGE(PG8_SA(0, 1), a2 + hA, voffA);
;             PG8_WAIT_V(8); PG8_WAIT_L(0); PG8_BAR; PG8_MMA(0, 0, At, B0); PG8_MMA(0, 1, At, B1); PG8_BAR; PG8_SCHED;
;             PG8_LDA(At, 1, 1); PG8_STAGE(PG8_SB(1, 0), b3, voffB); PG8_STAGE(PG8_SB(1, 1), b3 + hB, voffB); PG8_STAGE(PG8_SA(1, 0), a3, voffA);
;             PG8_WAIT_V(8); PG8_WAIT_L(0); PG8_BAR; PG8_MMA(1, 0, At, B0); PG8_MMA(1, 1, At, B1); PG8_BAR; PG8_SCHED;
	s_add_i32 s65, 0, 0x18000
	s_add_i32 s68, 0, 0x1c000
	v_add_u32_e32 v140, s65, v148
	v_add_u32_e32 v162, s68, v148
	ds_read_b128 v[120:123], v140
	ds_read_b128 v[124:127], v140 offset:1024
	ds_read_b128 v[136:139], v140 offset:2048
	ds_read_b128 v[140:143], v140 offset:3072
	ds_read_b128 v[150:153], v162
	ds_read_b128 v[154:157], v162 offset:1024
	ds_read_b128 v[158:161], v162 offset:2048
	ds_read_b128 v[162:165], v162 offset:3072
	s_add_u32 s66, s34, 0x40000
	s_mov_b32 m0, s47
	ds_read_b128 v[166:169], v149 offset:32768
	ds_read_b128 v[170:173], v149 offset:33792
	ds_read_b128 v[174:177], v149 offset:34816
	ds_read_b128 v[178:181], v149 offset:35840
	ds_read_b128 v[182:185], v149 offset:36864
	ds_read_b128 v[186:189], v149 offset:37888
	s_addc_u32 s67, s35, 0
	ds_read_b128 v[190:193], v149 offset:38912
	global_load_lds_dwordx4 v144, s[66:67]
	s_mov_b32 m0, s48
	ds_read_b128 v[194:197], v149 offset:39936
	global_load_lds_dwordx4 v147, s[66:67]
	s_waitcnt vmcnt(8)
	s_waitcnt lgkmcnt(0)
	s_barrier
	s_setprio 1
	s_waitcnt lgkmcnt(0)
	v_mfma_f32_16x16x32_bf16 v[128:131], v[120:123], v[166:169], v[128:131]
	v_mfma_f32_16x16x32_bf16 v[132:135], v[136:139], v[166:169], v[132:135]
	v_mfma_f32_16x16x32_bf16 v[116:119], v[120:123], v[174:177], v[116:119]
	v_mfma_f32_16x16x32_bf16 v[112:115], v[136:139], v[174:177], v[112:115]
	v_mfma_f32_16x16x32_bf16 v[108:111], v[120:123], v[182:185], v[108:111]
	v_mfma_f32_16x16x32_bf16 v[104:107], v[136:139], v[182:185], v[104:107]
	v_mfma_f32_16x16x32_bf16 v[100:103], v[120:123], v[190:193], v[100:103]
	v_mfma_f32_16x16x32_bf16 v[96:99], v[136:139], v[190:193], v[96:99]
	v_mfma_f32_16x16x32_bf16 v[128:131], v[124:127], v[170:173], v[128:131]
	v_mfma_f32_16x16x32_bf16 v[132:135], v[140:143], v[170:173], v[132:135]
	v_mfma_f32_16x16x32_bf16 v[116:119], v[124:127], v[178:181], v[116:119]
	v_mfma_f32_16x16x32_bf16 v[112:115], v[140:143], v[178:181], v[112:115]
	v_mfma_f32_16x16x32_bf16 v[108:111], v[124:127], v[186:189], v[108:111]
	v_mfma_f32_16x16x32_bf16 v[104:107], v[140:143], v[186:189], v[104:107]
	v_mfma_f32_16x16x32_bf16 v[100:103], v[124:127], v[194:197], v[100:103]
	v_mfma_f32_16x16x32_bf16 v[96:99], v[140:143], v[194:197], v[96:99]
	s_setprio 0
	s_setprio 1
	v_mfma_f32_16x16x32_bf16 v[60:63], v[150:153], v[166:169], v[60:63]
	v_mfma_f32_16x16x32_bf16 v[56:59], v[158:161], v[166:169], v[56:59]
	v_mfma_f32_16x16x32_bf16 v[52:55], v[150:153], v[174:177], v[52:55]
	v_mfma_f32_16x16x32_bf16 v[48:51], v[158:161], v[174:177], v[48:51]
	v_mfma_f32_16x16x32_bf16 v[44:47], v[150:153], v[182:185], v[44:47]
	v_mfma_f32_16x16x32_bf16 v[40:43], v[158:161], v[182:185], v[40:43]
	v_mfma_f32_16x16x32_bf16 v[36:39], v[150:153], v[190:193], v[36:39]
	v_mfma_f32_16x16x32_bf16 v[32:35], v[158:161], v[190:193], v[32:35]
	v_mfma_f32_16x16x32_bf16 v[60:63], v[154:157], v[170:173], v[60:63]
	v_mfma_f32_16x16x32_bf16 v[56:59], v[162:165], v[170:173], v[56:59]
	v_mfma_f32_16x16x32_bf16 v[52:55], v[154:157], v[178:181], v[52:55]
	v_mfma_f32_16x16x32_bf16 v[48:51], v[162:165], v[178:181], v[48:51]
	v_mfma_f32_16x16x32_bf16 v[44:47], v[154:157], v[186:189], v[44:47]
	v_mfma_f32_16x16x32_bf16 v[40:43], v[162:165], v[186:189], v[40:43]
	v_mfma_f32_16x16x32_bf16 v[36:39], v[154:157], v[194:197], v[36:39]
	v_mfma_f32_16x16x32_bf16 v[32:35], v[162:165], v[194:197], v[32:35]
	s_setprio 0
	s_barrier
	ds_read_b128 v[166:169], v149 offset:49152
	ds_read_b128 v[170:173], v149 offset:50176
	ds_read_b128 v[174:177], v149 offset:51200
	ds_read_b128 v[178:181], v149 offset:52224
	ds_read_b128 v[182:185], v149 offset:53248
	s_add_i32 s65, s65, s44
	s_add_u32 s100, s36, s2
	s_addc_u32 s101, s37, s3
	s_mov_b32 m0, s65
	ds_read_b128 v[186:189], v149 offset:54272
	global_load_lds_dwordx4 v145, s[100:101]
	s_add_i32 m0, s65, 0x2000
	s_add_u32 s100, s36, s2
	s_addc_u32 s101, s37, s3
	s_add_u32 s36, s36, 0x10080
	s_addc_u32 s37, s37, 0
	s_add_i32 s65, s68, s44
	global_load_lds_dwordx4 v146, s[100:101]
	s_mov_b32 m0, s65
	ds_read_b128 v[190:193], v149 offset:55296
	global_load_lds_dwordx4 v145, s[36:37]
	s_add_i32 m0, s65, 0x2000
	ds_read_b128 v[194:197], v149 offset:56320
	global_load_lds_dwordx4 v146, s[36:37]
	s_mov_b32 m0, s51
	s_add_u32 s100, s34, s2
	s_addc_u32 s101, s35, s3
	global_load_lds_dwordx4 v144, s[100:101]
	s_mov_b32 m0, s52
	s_add_u32 s100, s34, s2
	s_addc_u32 s101, s35, s3
	global_load_lds_dwordx4 v147, s[100:101]
	s_waitcnt vmcnt(8)
	s_waitcnt lgkmcnt(0)
	s_barrier
	s_setprio 1
	s_waitcnt lgkmcnt(0)
	v_mfma_f32_16x16x32_bf16 v[92:95], v[120:123], v[166:169], v[92:95]
	v_mfma_f32_16x16x32_bf16 v[88:91], v[136:139], v[166:169], v[88:91]
	v_mfma_f32_16x16x32_bf16 v[84:87], v[120:123], v[174:177], v[84:87]
	v_mfma_f32_16x16x32_bf16 v[80:83], v[136:139], v[174:177], v[80:83]
	v_mfma_f32_16x16x32_bf16 v[76:79], v[120:123], v[182:185], v[76:79]
	v_mfma_f32_16x16x32_bf16 v[72:75], v[136:139], v[182:185], v[72:75]
	v_mfma_f32_16x16x32_bf16 v[68:71], v[120:123], v[190:193], v[68:71]
	v_mfma_f32_16x16x32_bf16 v[64:67], v[136:139], v[190:193], v[64:67]
	v_mfma_f32_16x16x32_bf16 v[92:95], v[124:127], v[170:173], v[92:95]
	v_mfma_f32_16x16x32_bf16 v[88:91], v[140:143], v[170:173], v[88:91]
	v_mfma_f32_16x16x32_bf16 v[84:87], v[124:127], v[178:181], v[84:87]
	v_mfma_f32_16x16x32_bf16 v[80:83], v[140:143], v[178:181], v[80:83]
	v_mfma_f32_16x16x32_bf16 v[76:79], v[124:127], v[186:189], v[76:79]
	v_mfma_f32_16x16x32_bf16 v[72:75], v[140:143], v[186:189], v[72:75]
	v_mfma_f32_16x16x32_bf16 v[68:71], v[124:127], v[194:197], v[68:71]
	v_mfma_f32_16x16x32_bf16 v[64:67], v[140:143], v[194:197], v[64:67]
	s_setprio 0
	s_setprio 1
	v_mfma_f32_16x16x32_bf16 v[28:31], v[150:153], v[166:169], v[28:31]
	v_mfma_f32_16x16x32_bf16 v[24:27], v[158:161], v[166:169], v[24:27]
	v_mfma_f32_16x16x32_bf16 v[20:23], v[150:153], v[174:177], v[20:23]
	v_mfma_f32_16x16x32_bf16 v[16:19], v[158:161], v[174:177], v[16:19]
	v_mfma_f32_16x16x32_bf16 v[12:15], v[150:153], v[182:185], v[12:15]
	v_mfma_f32_16x16x32_bf16 v[8:11], v[158:161], v[182:185], v[8:11]
	v_mfma_f32_16x16x32_bf16 v[4:7], v[150:153], v[190:193], v[4:7]
	v_mfma_f32_16x16x32_bf16 v[0:3], v[158:161], v[190:193], v[0:3]
	v_mfma_f32_16x16x32_bf16 v[28:31], v[154:157], v[170:173], v[28:31]
	v_mfma_f32_16x16x32_bf16 v[24:27], v[162:165], v[170:173], v[24:27]
	v_mfma_f32_16x16x32_bf16 v[20:23], v[154:157], v[178:181], v[20:23]
	v_mfma_f32_16x16x32_bf16 v[16:19], v[162:165], v[178:181], v[16:19]
	v_mfma_f32_16x16x32_bf16 v[12:15], v[154:157], v[186:189], v[12:15]
	v_mfma_f32_16x16x32_bf16 v[8:11], v[162:165], v[186:189], v[8:11]
	v_mfma_f32_16x16x32_bf16 v[4:7], v[154:157], v[194:197], v[4:7]
	v_mfma_f32_16x16x32_bf16 v[0:3], v[162:165], v[194:197], v[0:3]
	s_setprio 0
	s_barrier
	s_add_u32 s26, s26, 0x100
	s_addc_u32 s27, s27, 0
	s_add_u32 s61, s61, 0x100
	s_addc_u32 s63, s63, 0
	s_cmp_ge_i32 s64, s53
	s_mov_b32 s34, s64
	s_cbranch_scc0 .LBB0_1503

; #define PG8_STAGE(bufoff, gbase, voff) do { _Pragma("unroll") for (int _i = 0; _i < 2; ++_i) \
;         { unsigned vo_ = (voff) + _i * voff##_d; asm volatile("" : "+v"(vo_)); __builtin_amdgcn_global_load_lds((const unsigned*)((const char*)(gbase) + vo_), (PG8_LAS unsigned*)(lds + (bufoff) + ldsw + _i * 8192), 16, 0, 0); } } while (0)
; #define PG8_LDA(dst, b, h) do { _Pragma("unroll") for (int m = 0; m < 4; ++m) _Pragma("unroll") for (int k = 0; k < 2; ++k) dst[m][k] = *(const PG8_LAS bf16x8*)(lds + PG8_SA(b, h) + aoff + m * 2048 + k * 1024); } while (0)
; #define PG8_LDB(dst, b, h) do { _Pragma("unroll") for (int n = 0; n < 2; ++n) _Pragma("unroll") for (int k = 0; k < 2; ++k) dst[n][k] = *(const PG8_LAS bf16x8*)(lds + PG8_SB(b, h) + boff + n * 2048 + k * 1024); } while (0)
; #define PG8_WAIT_V(n) asm volatile("s_waitcnt vmcnt(" #n ")" ::: "memory")
; #define PG8_WAIT_L(n) asm volatile("s_waitcnt lgkmcnt(" #n ")" ::: "memory")
; #define PG8_BAR __builtin_amdgcn_s_barrier()
; #define PG8_SCHED __builtin_amdgcn_sched_barrier(0)
; template <class Epi, class Sched, bool ALIGN_EPI, bool F8 = false>
; __device__ __forceinline__ void gemm_phase(PG8_LAS unsigned char* lds, const Gemm g, const Sched& S, const Epi& E, const int wid) {
;     ...
;             PG8_LDB(B0, 0, 0); PG8_LDB(B1, 0, 1); PG8_SCHED; PG8_LDA(At, 0, 0); PG8_STAGE(PG8_SA(1, 1), a1 + hA, voffA);
;             PG8_WAIT_V(8); PG8_WAIT_L(0); PG8_BAR; PG8_MMA(0, 0, At, B0); PG8_MMA(0, 1, At, B1); PG8_BAR; PG8_SCHED;
;             PG8_LDA(At, 0, 1); PG8_STAGE(PG8_SB(0, 0), b2, voffB); PG8_STAGE(PG8_SB(0, 1), b2 + hB, voffB); PG8_STAGE(PG8_SA(0, 0), a2, voffA);
;             PG8_WAIT_V(8); PG8_WAIT_L(0); PG8_BAR; PG8_MMA(1, 0, At, B0); PG8_MMA(1, 1, At, B1); PG8_BAR; PG8_SCHED;
;             PG8_LDB(B0, 1, 0); PG8_LDB(B1, 1, 1); PG8_SCHED; PG8_LDA(At, 1, 0); PG8_STAGE(PG8_SA(0, 1), a2 + hA, voffA);
;             PG8_WAIT_V(8); PG8_WAIT_L(0); PG8_BAR; PG8_MMA(0, 0, At, B0); PG8_MMA(0, 1, At, B1); PG8_BAR; PG8_SCHED;
.LBB0_1770:
	s_add_i32 s59, s28, 2
	s_add_u32 s30, s26, 0xfffe0080
	s_addc_u32 s29, s27, -1
	s_add_i32 s60, 0, 0x10000
	s_cmp_eq_u32 s51, s28
	s_cselect_b32 s29, s13, s29
	s_cselect_b32 s28, s15, s30
	s_cselect_b32 s31, s55, s58
	s_cselect_b32 s30, s56, s57
	s_add_i32 s62, 0, 0x14000
	v_add_u32_e32 v140, s60, v186
	v_add_u32_e32 v156, s62, v186
	ds_read_b128 v[128:131], v140
	ds_read_b128 v[132:135], v140 offset:1024
	ds_read_b128 v[136:139], v140 offset:2048
	ds_read_b128 v[140:143], v140 offset:3072
	ds_read_b128 v[144:147], v156
	ds_read_b128 v[148:151], v156 offset:1024
	ds_read_b128 v[152:155], v156 offset:2048
	ds_read_b128 v[156:159], v156 offset:3072
	ds_read_b128 v[160:163], v187
	ds_read_b128 v[164:167], v187 offset:1024
	ds_read_b128 v[168:171], v187 offset:2048
	ds_read_b128 v[172:175], v187 offset:3072
	ds_read_b128 v[188:191], v187 offset:4096
	ds_read_b128 v[192:195], v187 offset:5120
	s_add_i32 m0, s40, 0xc000
	ds_read_b128 v[206:209], v187 offset:6144
	global_load_lds_dwordx4 v182, s[26:27]
	s_add_i32 m0, s40, 0xe000
	ds_read_b128 v[210:213], v187 offset:7168
	global_load_lds_dwordx4 v185, s[26:27]
	s_waitcnt vmcnt(8)
	s_waitcnt lgkmcnt(0)
	s_barrier
	s_setprio 1
	s_waitcnt lgkmcnt(0)
	v_mfma_f32_16x16x128_f8f6f4 v[124:127], v[128:135], v[160:167], v[124:127]
	v_mfma_f32_16x16x128_f8f6f4 v[120:123], v[136:143], v[160:167], v[120:123]
	v_mfma_f32_16x16x128_f8f6f4 v[116:119], v[128:135], v[168:175], v[116:119]
	v_mfma_f32_16x16x128_f8f6f4 v[112:115], v[136:143], v[168:175], v[112:115]
	v_mfma_f32_16x16x128_f8f6f4 v[104:107], v[128:135], v[188:195], v[104:107]
	v_mfma_f32_16x16x128_f8f6f4 v[176:179], v[136:143], v[188:195], v[96:99]
	v_mfma_f32_16x16x128_f8f6f4 v[196:199], v[128:135], v[206:213], v[88:91]
	v_mfma_f32_16x16x128_f8f6f4 v[202:205], v[136:143], v[206:213], v[80:83]
	s_setprio 0
	s_setprio 1
	v_mfma_f32_16x16x128_f8f6f4 v[108:111], v[144:151], v[160:167], v[108:111]
	v_mfma_f32_16x16x128_f8f6f4 v[100:103], v[152:159], v[160:167], v[100:103]
	v_mfma_f32_16x16x128_f8f6f4 v[60:63], v[152:159], v[206:213], v[60:63]
	v_mfma_f32_16x16x128_f8f6f4 v[160:163], v[144:151], v[168:175], v[92:95]
	v_mfma_f32_16x16x128_f8f6f4 v[164:167], v[152:159], v[168:175], v[84:87]
	v_mfma_f32_16x16x128_f8f6f4 v[168:171], v[144:151], v[188:195], v[76:79]
	v_mfma_f32_16x16x128_f8f6f4 v[172:175], v[152:159], v[188:195], v[72:75]
	v_mfma_f32_16x16x128_f8f6f4 v[188:191], v[144:151], v[206:213], v[68:71]
	s_setprio 0
	s_barrier
	s_add_i32 s60, s60, s39
	s_nop 2
	ds_read_b128 v[68:71], v187 offset:16384
	ds_read_b128 v[72:75], v187 offset:17408
	ds_read_b128 v[76:79], v187 offset:18432
	s_mov_b32 m0, s60
	ds_read_b128 v[80:83], v187 offset:19456
	global_load_lds_dwordx4 v183, s[30:31]
	s_add_i32 m0, s60, 0x2000
	s_add_u32 s60, s30, 0x20000
	global_load_lds_dwordx4 v184, s[30:31]
	s_addc_u32 s61, s31, 0
	s_add_i32 s62, s62, s39
	s_mov_b32 m0, s62
	ds_read_b128 v[84:87], v187 offset:20480
	global_load_lds_dwordx4 v183, s[60:61]
	s_add_i32 m0, s62, 0x2000
	ds_read_b128 v[88:91], v187 offset:21504
	global_load_lds_dwordx4 v184, s[60:61]
	s_mov_b32 m0, s40
	ds_read_b128 v[92:95], v187 offset:22528
	global_load_lds_dwordx4 v182, s[28:29]
	s_mov_b32 m0, s41
	ds_read_b128 v[96:99], v187 offset:23552
	global_load_lds_dwordx4 v185, s[28:29]
	s_waitcnt vmcnt(8)
	s_waitcnt lgkmcnt(0)
	s_barrier
	s_setprio 1
	s_waitcnt lgkmcnt(0)
	v_mfma_f32_16x16x128_f8f6f4 v[64:67], v[128:135], v[68:75], v[64:67]
	v_mfma_f32_16x16x128_f8f6f4 v[56:59], v[136:143], v[68:75], v[56:59]
	v_mfma_f32_16x16x128_f8f6f4 v[52:55], v[128:135], v[76:83], v[52:55]
	v_mfma_f32_16x16x128_f8f6f4 v[48:51], v[136:143], v[76:83], v[48:51]
	v_mfma_f32_16x16x128_f8f6f4 v[192:195], v[128:135], v[84:91], v[40:43]
	v_mfma_f32_16x16x128_f8f6f4 v[206:209], v[136:143], v[84:91], v[32:35]
	v_mfma_f32_16x16x128_f8f6f4 v[210:213], v[128:135], v[92:99], v[24:27]
	v_mfma_f32_16x16x128_f8f6f4 v[214:217], v[136:143], v[92:99], v[16:19]
	s_setprio 0
	s_setprio 1
	v_mfma_f32_16x16x128_f8f6f4 v[218:221], v[144:151], v[68:75], v[44:47]
	v_mfma_f32_16x16x128_f8f6f4 v[224:227], v[152:159], v[68:75], v[36:39]
	v_mfma_f32_16x16x128_f8f6f4 v[228:231], v[144:151], v[76:83], v[28:31]
	v_mfma_f32_16x16x128_f8f6f4 v[232:235], v[152:159], v[76:83], v[20:23]
	v_mfma_f32_16x16x128_f8f6f4 v[236:239], v[144:151], v[84:91], v[12:15]
	v_mfma_f32_16x16x128_f8f6f4 v[242:245], v[152:159], v[84:91], v[8:11]
	v_mfma_f32_16x16x128_f8f6f4 v[246:249], v[144:151], v[92:99], v[4:7]
	v_mfma_f32_16x16x128_f8f6f4 v[250:253], v[152:159], v[92:99], v[0:3]
	s_setprio 0
	s_barrier
	s_add_i32 s62, 0, 0x18000
	s_add_i32 s63, 0, 0x1c000
	v_add_u32_e32 v12, s62, v186
	v_add_u32_e32 v16, s63, v186
	s_nop 0
	ds_read_b128 v[0:3], v12
	ds_read_b128 v[4:7], v12 offset:1024
	ds_read_b128 v[8:11], v12 offset:2048
	ds_read_b128 v[12:15], v12 offset:3072
	ds_read_b128 v[128:131], v16
	ds_read_b128 v[132:135], v16 offset:1024
	ds_read_b128 v[136:139], v16 offset:2048
	ds_read_b128 v[140:143], v16 offset:3072
	s_add_u32 s60, s28, 0x20000
	s_mov_b32 m0, s42
	ds_read_b128 v[16:19], v187 offset:32768
	ds_read_b128 v[20:23], v187 offset:33792
	ds_read_b128 v[24:27], v187 offset:34816
	ds_read_b128 v[28:31], v187 offset:35840
	ds_read_b128 v[32:35], v187 offset:36864
	ds_read_b128 v[36:39], v187 offset:37888
	s_addc_u32 s61, s29, 0
	ds_read_b128 v[40:43], v187 offset:38912
	global_load_lds_dwordx4 v182, s[60:61]
	s_mov_b32 m0, s43
	ds_read_b128 v[44:47], v187 offset:39936
	global_load_lds_dwordx4 v185, s[60:61]
	s_waitcnt vmcnt(8)
	s_waitcnt lgkmcnt(0)
	s_barrier
; #define PG8_STAGE(bufoff, gbase, voff) do { _Pragma("unroll") for (int _i = 0; _i < 2; ++_i) \
;         { unsigned vo_ = (voff) + _i * voff##_d; asm volatile("" : "+v"(vo_)); __builtin_amdgcn_global_load_lds((const unsigned*)((const char*)(gbase) + vo_), (PG8_LAS unsigned*)(lds + (bufoff) + ldsw + _i * 8192), 16, 0, 0); } } while (0)
; #define PG8_LDA(dst, b, h) do { _Pragma("unroll") for (int m = 0; m < 4; ++m) _Pragma("unroll") for (int k = 0; k < 2; ++k) dst[m][k] = *(const PG8_LAS bf16x8*)(lds + PG8_SA(b, h) + aoff + m * 2048 + k * 1024); } while (0)
; #define PG8_WAIT_V(n) asm volatile("s_waitcnt vmcnt(" #n ")" ::: "memory")
; #define PG8_WAIT_L(n) asm volatile("s_waitcnt lgkmcnt(" #n ")" ::: "memory")
; #define PG8_BAR __builtin_amdgcn_s_barrier()
; #define PG8_SCHED __builtin_amdgcn_sched_barrier(0)
; template <class Epi, class Sched, bool ALIGN_EPI, bool F8 = false>
; __device__ __forceinline__ void gemm_phase(PG8_LAS unsigned char* lds, const Gemm g, const Sched& S, const Epi& E, const int wid) {
;     ...
;             PG8_WAIT_V(8); PG8_WAIT_L(0); PG8_BAR; PG8_MMA(0, 0, At, B0); PG8_MMA(0, 1, At, B1); PG8_BAR; PG8_SCHED;
;             PG8_LDA(At, 1, 1); PG8_STAGE(PG8_SB(1, 0), b3, voffB); PG8_STAGE(PG8_SB(1, 1), b3 + hB, voffB); PG8_STAGE(PG8_SA(1, 0), a3, voffA);
;             PG8_WAIT_V(8); PG8_WAIT_L(0); PG8_BAR; PG8_MMA(1, 0, At, B0); PG8_MMA(1, 1, At, B1); PG8_BAR; PG8_SCHED;
	s_setprio 1
	s_waitcnt lgkmcnt(0)
	v_mfma_f32_16x16x128_f8f6f4 v[124:127], v[0:7], v[16:23], v[124:127]
	v_mfma_f32_16x16x128_f8f6f4 v[120:123], v[8:15], v[16:23], v[120:123]
	v_mfma_f32_16x16x128_f8f6f4 v[116:119], v[0:7], v[24:31], v[116:119]
	v_mfma_f32_16x16x128_f8f6f4 v[112:115], v[8:15], v[24:31], v[112:115]
	v_mfma_f32_16x16x128_f8f6f4 v[104:107], v[0:7], v[32:39], v[104:107]
	v_mfma_f32_16x16x128_f8f6f4 v[96:99], v[8:15], v[32:39], v[176:179]
	v_mfma_f32_16x16x128_f8f6f4 v[88:91], v[0:7], v[40:47], v[196:199]
	v_mfma_f32_16x16x128_f8f6f4 v[80:83], v[8:15], v[40:47], v[202:205]
	s_setprio 0
	s_setprio 1
	v_mfma_f32_16x16x128_f8f6f4 v[108:111], v[128:135], v[16:23], v[108:111]
	v_mfma_f32_16x16x128_f8f6f4 v[100:103], v[136:143], v[16:23], v[100:103]
	v_mfma_f32_16x16x128_f8f6f4 v[92:95], v[128:135], v[24:31], v[160:163]
	v_mfma_f32_16x16x128_f8f6f4 v[84:87], v[136:143], v[24:31], v[164:167]
	v_mfma_f32_16x16x128_f8f6f4 v[76:79], v[128:135], v[32:39], v[168:171]
	v_mfma_f32_16x16x128_f8f6f4 v[72:75], v[136:143], v[32:39], v[172:175]
	v_mfma_f32_16x16x128_f8f6f4 v[68:71], v[128:135], v[40:47], v[188:191]
	v_mfma_f32_16x16x128_f8f6f4 v[60:63], v[136:143], v[40:47], v[60:63]
	s_setprio 0
	s_barrier
	ds_read_b128 v[144:147], v187 offset:49152
	ds_read_b128 v[148:151], v187 offset:50176
	ds_read_b128 v[152:155], v187 offset:51200
	ds_read_b128 v[156:159], v187 offset:52224
	ds_read_b128 v[160:163], v187 offset:53248
	s_add_i32 s60, s62, s39
	s_add_u32 s100, s30, s2
	s_addc_u32 s101, s31, s3
	s_mov_b32 m0, s60
	ds_read_b128 v[164:167], v187 offset:54272
	global_load_lds_dwordx4 v183, s[100:101]
	s_add_i32 m0, s60, 0x2000
	s_add_u32 s100, s30, s2
	s_addc_u32 s101, s31, s3
	s_add_u32 s30, s30, 0x20080
	global_load_lds_dwordx4 v184, s[100:101]
	s_addc_u32 s31, s31, 0
	s_add_i32 s60, s63, s39
	s_mov_b32 m0, s60
	ds_read_b128 v[168:171], v187 offset:55296
	global_load_lds_dwordx4 v183, s[30:31]
	s_add_i32 m0, s60, 0x2000
	ds_read_b128 v[172:175], v187 offset:56320
	global_load_lds_dwordx4 v184, s[30:31]
	s_mov_b32 m0, s49
	s_add_u32 s100, s28, s2
	s_addc_u32 s101, s29, s3
	global_load_lds_dwordx4 v182, s[100:101]
	s_mov_b32 m0, s50
	s_add_u32 s100, s28, s2
	s_addc_u32 s101, s29, s3
	global_load_lds_dwordx4 v185, s[100:101]
	s_waitcnt vmcnt(8)
	s_waitcnt lgkmcnt(0)
	s_barrier
	s_setprio 1
	s_waitcnt lgkmcnt(0)
	v_mfma_f32_16x16x128_f8f6f4 v[64:67], v[0:7], v[144:151], v[64:67]
	v_mfma_f32_16x16x128_f8f6f4 v[56:59], v[8:15], v[144:151], v[56:59]
	v_mfma_f32_16x16x128_f8f6f4 v[52:55], v[0:7], v[152:159], v[52:55]
	v_mfma_f32_16x16x128_f8f6f4 v[48:51], v[8:15], v[152:159], v[48:51]
	v_mfma_f32_16x16x128_f8f6f4 v[40:43], v[0:7], v[160:167], v[192:195]
	v_mfma_f32_16x16x128_f8f6f4 v[32:35], v[8:15], v[160:167], v[206:209]
	v_mfma_f32_16x16x128_f8f6f4 v[24:27], v[0:7], v[168:175], v[210:213]
	v_mfma_f32_16x16x128_f8f6f4 v[16:19], v[8:15], v[168:175], v[214:217]
	s_setprio 0
	s_setprio 1
	v_mfma_f32_16x16x128_f8f6f4 v[44:47], v[128:135], v[144:151], v[218:221]
	v_mfma_f32_16x16x128_f8f6f4 v[36:39], v[136:143], v[144:151], v[224:227]
	v_mfma_f32_16x16x128_f8f6f4 v[28:31], v[128:135], v[152:159], v[228:231]
	v_mfma_f32_16x16x128_f8f6f4 v[20:23], v[136:143], v[152:159], v[232:235]
	v_mfma_f32_16x16x128_f8f6f4 v[12:15], v[128:135], v[160:167], v[236:239]
	v_mfma_f32_16x16x128_f8f6f4 v[8:11], v[136:143], v[160:167], v[242:245]
	v_mfma_f32_16x16x128_f8f6f4 v[4:7], v[128:135], v[168:175], v[246:249]
	v_mfma_f32_16x16x128_f8f6f4 v[0:3], v[136:143], v[168:175], v[250:253]
	s_setprio 0
	s_barrier
	s_add_u32 s26, s26, 0x100
	s_addc_u32 s27, s27, 0
	s_add_u32 s57, s57, 0x100
	s_addc_u32 s58, s58, 0
	s_cmp_ge_i32 s59, s46
	s_mov_b32 s28, s59
	s_cbranch_scc0 .LBB0_1770
; __device__ __forceinline__ unsigned pk2(float lo, float hi) { typedef float f2_ __attribute__((ext_vector_type(2))); const bf16x2n_t b = __builtin_convertvector((f2_){lo, hi}, bf16x2n_t); return __builtin_bit_cast(unsigned, b); }
; __device__ __forceinline__ float gate_u8(unsigned w, int k) { return __builtin_fmaf((float)((w >> (8 * k)) & 0xffu), 1.0f / 255.0f, 0.5f / 255.0f); }
;     __device__ __forceinline__ void operator()(const f32x4 (&acc)[2][2][4][2], const pg8::Unit& u, int wr, int wc, int fr, int fq) const {
;     ...
;                 for (int bj = 0; bj < 2; ++bj) { const u32x2 g = gg[ai][m][bj];
;                     const f32x4 v0 = acc[ai][bj][m][0] * (1.0f / 32.0f), v1 = acc[ai][bj][m][1] * (1.0f / 32.0f);
;                     u32x4 w; w.x = pk2(v0[0] * gate_u8(g.x, 0), v0[1] * gate_u8(g.x, 1)); w.y = pk2(v0[2] * gate_u8(g.x, 2), v0[3] * gate_u8(g.x, 3)); w.z = pk2(v1[0] * gate_u8(g.y, 0), v1[1] * gate_u8(g.y, 1)); w.w = pk2(v1[2] * gate_u8(g.y, 2), v1[3] * gate_u8(g.y, 3));
	s_mov_b32 s26, 0x3d000000
	v_pk_mul_f32 v[148:149], v[126:127], s[26:27] op_sel_hi:[1,0]
	v_pk_mul_f32 v[156:157], v[124:125], s[26:27] op_sel_hi:[1,0]
	v_pk_mul_f32 v[152:153], v[122:123], s[26:27] op_sel_hi:[1,0]
	v_pk_mul_f32 v[154:155], v[120:121], s[26:27] op_sel_hi:[1,0]
	v_pk_mul_f32 v[126:127], v[110:111], s[26:27] op_sel_hi:[1,0]
	v_pk_mul_f32 v[130:131], v[108:109], s[26:27] op_sel_hi:[1,0]
	v_pk_mul_f32 v[124:125], v[102:103], s[26:27] op_sel_hi:[1,0]
	v_pk_mul_f32 v[128:129], v[100:101], s[26:27] op_sel_hi:[1,0]
	v_pk_mul_f32 v[118:119], v[118:119], s[26:27] op_sel_hi:[1,0]
	v_pk_mul_f32 v[122:123], v[116:117], s[26:27] op_sel_hi:[1,0]
	v_pk_mul_f32 v[110:111], v[114:115], s[26:27] op_sel_hi:[1,0]
	v_pk_mul_f32 v[116:117], v[112:113], s[26:27] op_sel_hi:[1,0]
	v_pk_mul_f32 v[112:113], v[94:95], s[26:27] op_sel_hi:[1,0]
	v_pk_mul_f32 v[120:121], v[92:93], s[26:27] op_sel_hi:[1,0]
	v_pk_mul_f32 v[108:109], v[86:87], s[26:27] op_sel_hi:[1,0]
	v_pk_mul_f32 v[114:115], v[84:85], s[26:27] op_sel_hi:[1,0]
	v_pk_mul_f32 v[100:101], v[106:107], s[26:27] op_sel_hi:[1,0]
	v_pk_mul_f32 v[106:107], v[104:105], s[26:27] op_sel_hi:[1,0]
	v_pk_mul_f32 v[94:95], v[98:99], s[26:27] op_sel_hi:[1,0]
	v_pk_mul_f32 v[102:103], v[96:97], s[26:27] op_sel_hi:[1,0]
	v_pk_mul_f32 v[96:97], v[78:79], s[26:27] op_sel_hi:[1,0]
	v_pk_mul_f32 v[104:105], v[76:77], s[26:27] op_sel_hi:[1,0]
	v_pk_mul_f32 v[92:93], v[74:75], s[26:27] op_sel_hi:[1,0]
	v_pk_mul_f32 v[98:99], v[72:73], s[26:27] op_sel_hi:[1,0]
	v_pk_mul_f32 v[84:85], v[90:91], s[26:27] op_sel_hi:[1,0]
	v_pk_mul_f32 v[90:91], v[88:89], s[26:27] op_sel_hi:[1,0]
	v_pk_mul_f32 v[78:79], v[82:83], s[26:27] op_sel_hi:[1,0]
	v_pk_mul_f32 v[86:87], v[80:81], s[26:27] op_sel_hi:[1,0]
	v_pk_mul_f32 v[80:81], v[70:71], s[26:27] op_sel_hi:[1,0]
	v_pk_mul_f32 v[88:89], v[68:69], s[26:27] op_sel_hi:[1,0]
	v_pk_mul_f32 v[76:77], v[62:63], s[26:27] op_sel_hi:[1,0]
	v_pk_mul_f32 v[82:83], v[60:61], s[26:27] op_sel_hi:[1,0]
	v_pk_mul_f32 v[68:69], v[66:67], s[26:27] op_sel_hi:[1,0]
	v_pk_mul_f32 v[74:75], v[64:65], s[26:27] op_sel_hi:[1,0]
	v_pk_mul_f32 v[62:63], v[58:59], s[26:27] op_sel_hi:[1,0]
	v_pk_mul_f32 v[70:71], v[56:57], s[26:27] op_sel_hi:[1,0]
	v_pk_mul_f32 v[64:65], v[46:47], s[26:27] op_sel_hi:[1,0]
	v_pk_mul_f32 v[72:73], v[44:45], s[26:27] op_sel_hi:[1,0]
	v_pk_mul_f32 v[60:61], v[38:39], s[26:27] op_sel_hi:[1,0]
	v_pk_mul_f32 v[66:67], v[36:37], s[26:27] op_sel_hi:[1,0]
	v_pk_mul_f32 v[54:55], v[54:55], s[26:27] op_sel_hi:[1,0]
	v_pk_mul_f32 v[58:59], v[52:53], s[26:27] op_sel_hi:[1,0]
	v_pk_mul_f32 v[46:47], v[50:51], s[26:27] op_sel_hi:[1,0]
	v_pk_mul_f32 v[52:53], v[48:49], s[26:27] op_sel_hi:[1,0]
	v_pk_mul_f32 v[48:49], v[30:31], s[26:27] op_sel_hi:[1,0]
	v_pk_mul_f32 v[56:57], v[28:29], s[26:27] op_sel_hi:[1,0]
	v_pk_mul_f32 v[44:45], v[22:23], s[26:27] op_sel_hi:[1,0]
	v_pk_mul_f32 v[50:51], v[20:21], s[26:27] op_sel_hi:[1,0]
	v_pk_mul_f32 v[36:37], v[42:43], s[26:27] op_sel_hi:[1,0]
	v_pk_mul_f32 v[40:41], v[40:41], s[26:27] op_sel_hi:[1,0]
	v_pk_mul_f32 v[28:29], v[34:35], s[26:27] op_sel_hi:[1,0]
	v_pk_mul_f32 v[34:35], v[32:33], s[26:27] op_sel_hi:[1,0]
	v_pk_mul_f32 v[30:31], v[14:15], s[26:27] op_sel_hi:[1,0]
	v_pk_mul_f32 v[38:39], v[12:13], s[26:27] op_sel_hi:[1,0]
	v_pk_mul_f32 v[22:23], v[10:11], s[26:27] op_sel_hi:[1,0]
	v_pk_mul_f32 v[32:33], v[8:9], s[26:27] op_sel_hi:[1,0]
	v_pk_mul_f32 v[12:13], v[26:27], s[26:27] op_sel_hi:[1,0]
	v_pk_mul_f32 v[20:21], v[24:25], s[26:27] op_sel_hi:[1,0]
	v_pk_mul_f32 v[8:9], v[18:19], s[26:27] op_sel_hi:[1,0]
	v_pk_mul_f32 v[14:15], v[16:17], s[26:27] op_sel_hi:[1,0]
	v_pk_mul_f32 v[6:7], v[6:7], s[26:27] op_sel_hi:[1,0]
	v_pk_mul_f32 v[16:17], v[4:5], s[26:27] op_sel_hi:[1,0]
	v_pk_mul_f32 v[4:5], v[2:3], s[26:27] op_sel_hi:[1,0]
	v_pk_mul_f32 v[10:11], v[0:1], s[26:27] op_sel_hi:[1,0]
	v_mov_b32_e32 v232, v181
	v_mov_b32_e32 v233, v223
	v_mov_b32_e32 v223, 0x260
	v_mov_b32_e32 v234, 0x1e000
	v_mov_b32_e32 v235, 0x7f800000
	v_mov_b32_e32 v236, 0x7fc00000
	v_mov_b32_e32 v237, 0x7fffff
	v_mov_b64_e32 v[238:239], 0x140
	v_mov_b64_e32 v[252:253], 0x13f
	v_mov_b32_e32 v198, 23

; #define PG8_STAGE(bufoff, gbase, voff) do { _Pragma("unroll") for (int _i = 0; _i < 2; ++_i) \
;         { unsigned vo_ = (voff) + _i * voff##_d; asm volatile("" : "+v"(vo_)); __builtin_amdgcn_global_load_lds((const unsigned*)((const char*)(gbase) + vo_), (PG8_LAS unsigned*)(lds + (bufoff) + ldsw + _i * 8192), 16, 0, 0); } } while (0)
; #define PG8_LDA(dst, b, h) do { _Pragma("unroll") for (int m = 0; m < 4; ++m) _Pragma("unroll") for (int k = 0; k < 2; ++k) dst[m][k] = *(const PG8_LAS bf16x8*)(lds + PG8_SA(b, h) + aoff + m * 2048 + k * 1024); } while (0)
; #define PG8_LDB(dst, b, h) do { _Pragma("unroll") for (int n = 0; n < 2; ++n) _Pragma("unroll") for (int k = 0; k < 2; ++k) dst[n][k] = *(const PG8_LAS bf16x8*)(lds + PG8_SB(b, h) + boff + n * 2048 + k * 1024); } while (0)
; #define PG8_WAIT_V(n) asm volatile("s_waitcnt vmcnt(" #n ")" ::: "memory")
; #define PG8_WAIT_L(n) asm volatile("s_waitcnt lgkmcnt(" #n ")" ::: "memory")
; #define PG8_BAR __builtin_amdgcn_s_barrier()
; #define PG8_SCHED __builtin_amdgcn_sched_barrier(0)
; template <class Epi, class Sched, bool ALIGN_EPI, bool F8 = false>
; __device__ __forceinline__ void gemm_phase(PG8_LAS unsigned char* lds, const Gemm g, const Sched& S, const Epi& E, const int wid) {
;     ...
;             PG8_LDB(B0, 0, 0); PG8_LDB(B1, 0, 1); PG8_SCHED; PG8_LDA(At, 0, 0); PG8_STAGE(PG8_SA(1, 1), a1 + hA, voffA);
;             PG8_WAIT_V(8); PG8_WAIT_L(0); PG8_BAR; PG8_MMA(0, 0, At, B0); PG8_MMA(0, 1, At, B1); PG8_BAR; PG8_SCHED;
;             PG8_LDA(At, 0, 1); PG8_STAGE(PG8_SB(0, 0), b2, voffB); PG8_STAGE(PG8_SB(0, 1), b2 + hB, voffB); PG8_STAGE(PG8_SA(0, 0), a2, voffA);
;             PG8_WAIT_V(8); PG8_WAIT_L(0); PG8_BAR; PG8_MMA(1, 0, At, B0); PG8_MMA(1, 1, At, B1); PG8_BAR; PG8_SCHED;
.LBB0_1851:
	s_add_i32 s76, s48, 2
	s_add_u32 s50, s46, 0xfff80080
	s_addc_u32 s49, s47, -1
	s_add_i32 s77, 0, 0x10000
	s_cmp_eq_u32 s69, s48
	s_cselect_b32 s49, s23, s49
	s_cselect_b32 s48, s25, s50
	s_cselect_b32 s51, s72, s75
	s_cselect_b32 s50, s73, s74
	s_add_i32 s80, 0, 0x14000
	v_add_u32_e32 v140, s77, v243
	v_add_u32_e32 v156, s80, v243
	ds_read_b128 v[128:131], v140
	ds_read_b128 v[132:135], v140 offset:1024
	ds_read_b128 v[136:139], v140 offset:2048
	ds_read_b128 v[140:143], v140 offset:3072
	ds_read_b128 v[144:147], v156
	ds_read_b128 v[148:151], v156 offset:1024
	ds_read_b128 v[152:155], v156 offset:2048
	ds_read_b128 v[156:159], v156 offset:3072
	ds_read_b128 v[160:163], v244
	ds_read_b128 v[164:167], v244 offset:1024
	ds_read_b128 v[168:171], v244 offset:2048
	ds_read_b128 v[174:177], v244 offset:3072
	ds_read_b128 v[178:181], v244 offset:4096
	ds_read_b128 v[182:185], v244 offset:5120
	s_add_i32 m0, s60, 0xc000
	ds_read_b128 v[186:189], v244 offset:6144
	global_load_lds_dwordx4 v173, s[46:47]
	s_add_i32 m0, s60, 0xe000
	ds_read_b128 v[190:193], v244 offset:7168
	global_load_lds_dwordx4 v242, s[46:47]
	s_waitcnt vmcnt(8)
	s_waitcnt lgkmcnt(0)
	s_barrier
	s_setprio 1
	s_waitcnt lgkmcnt(0)
	v_mfma_f32_16x16x32_bf16 v[124:127], v[128:131], v[160:163], v[124:127]
	v_mfma_f32_16x16x32_bf16 v[120:123], v[136:139], v[160:163], v[120:123]
	v_mfma_f32_16x16x32_bf16 v[108:111], v[128:131], v[168:171], v[108:111]
	v_mfma_f32_16x16x32_bf16 v[104:107], v[136:139], v[168:171], v[104:107]
	v_mfma_f32_16x16x32_bf16 v[92:95], v[128:131], v[178:181], v[92:95]
	v_mfma_f32_16x16x32_bf16 v[88:91], v[136:139], v[178:181], v[88:91]
	v_mfma_f32_16x16x32_bf16 v[76:79], v[128:131], v[186:189], v[76:79]
	v_mfma_f32_16x16x32_bf16 v[72:75], v[136:139], v[186:189], v[72:75]
	v_mfma_f32_16x16x32_bf16 v[124:127], v[132:135], v[164:167], v[124:127]
	v_mfma_f32_16x16x32_bf16 v[120:123], v[140:143], v[164:167], v[120:123]
	v_mfma_f32_16x16x32_bf16 v[108:111], v[132:135], v[174:177], v[108:111]
	v_mfma_f32_16x16x32_bf16 v[104:107], v[140:143], v[174:177], v[104:107]
	v_mfma_f32_16x16x32_bf16 v[92:95], v[132:135], v[182:185], v[92:95]
	v_mfma_f32_16x16x32_bf16 v[88:91], v[140:143], v[182:185], v[88:91]
	v_mfma_f32_16x16x32_bf16 v[76:79], v[132:135], v[190:193], v[76:79]
	v_mfma_f32_16x16x32_bf16 v[72:75], v[140:143], v[190:193], v[72:75]
	s_setprio 0
	s_setprio 1
	v_mfma_f32_16x16x32_bf16 v[116:119], v[144:147], v[160:163], v[116:119]
	v_mfma_f32_16x16x32_bf16 v[112:115], v[152:155], v[160:163], v[112:115]
	v_mfma_f32_16x16x32_bf16 v[100:103], v[144:147], v[168:171], v[100:103]
	v_mfma_f32_16x16x32_bf16 v[96:99], v[152:155], v[168:171], v[96:99]
	v_mfma_f32_16x16x32_bf16 v[84:87], v[144:147], v[178:181], v[84:87]
	v_mfma_f32_16x16x32_bf16 v[80:83], v[152:155], v[178:181], v[80:83]
	v_mfma_f32_16x16x32_bf16 v[68:71], v[144:147], v[186:189], v[68:71]
	v_mfma_f32_16x16x32_bf16 v[64:67], v[152:155], v[186:189], v[64:67]
	v_mfma_f32_16x16x32_bf16 v[116:119], v[148:151], v[164:167], v[116:119]
	v_mfma_f32_16x16x32_bf16 v[112:115], v[156:159], v[164:167], v[112:115]
	v_mfma_f32_16x16x32_bf16 v[100:103], v[148:151], v[174:177], v[100:103]
	v_mfma_f32_16x16x32_bf16 v[96:99], v[156:159], v[174:177], v[96:99]
	v_mfma_f32_16x16x32_bf16 v[84:87], v[148:151], v[182:185], v[84:87]
	v_mfma_f32_16x16x32_bf16 v[80:83], v[156:159], v[182:185], v[80:83]
	v_mfma_f32_16x16x32_bf16 v[68:71], v[148:151], v[190:193], v[68:71]
	v_mfma_f32_16x16x32_bf16 v[64:67], v[156:159], v[190:193], v[64:67]
	s_setprio 0
	s_barrier
	s_add_i32 s77, s77, s58
	ds_read_b128 v[160:163], v244 offset:16384
	ds_read_b128 v[164:167], v244 offset:17408
	ds_read_b128 v[168:171], v244 offset:18432
	s_mov_b32 m0, s77
	ds_read_b128 v[174:177], v244 offset:19456
	global_load_lds_dwordx4 v173, s[50:51]
	s_add_i32 m0, s77, 0x2000
	s_add_u32 s78, s50, 0x80000
	global_load_lds_dwordx4 v242, s[50:51]
	s_addc_u32 s79, s51, 0
	s_add_i32 s77, s80, s58
	s_mov_b32 m0, s77
	ds_read_b128 v[178:181], v244 offset:20480
	global_load_lds_dwordx4 v173, s[78:79]
	s_add_i32 m0, s77, 0x2000
	ds_read_b128 v[182:185], v244 offset:21504
	global_load_lds_dwordx4 v242, s[78:79]
	s_mov_b32 m0, s60
	ds_read_b128 v[186:189], v244 offset:22528
	global_load_lds_dwordx4 v173, s[48:49]
	s_mov_b32 m0, s61
	ds_read_b128 v[190:193], v244 offset:23552
	global_load_lds_dwordx4 v242, s[48:49]
	s_waitcnt vmcnt(8)
	s_waitcnt lgkmcnt(0)
	s_barrier
	s_setprio 1
	s_waitcnt lgkmcnt(0)
	v_mfma_f32_16x16x32_bf16 v[60:63], v[128:131], v[160:163], v[60:63]
	v_mfma_f32_16x16x32_bf16 v[56:59], v[136:139], v[160:163], v[56:59]
	v_mfma_f32_16x16x32_bf16 v[44:47], v[128:131], v[168:171], v[44:47]
	v_mfma_f32_16x16x32_bf16 v[40:43], v[136:139], v[168:171], v[40:43]
	v_mfma_f32_16x16x32_bf16 v[28:31], v[128:131], v[178:181], v[28:31]
	v_mfma_f32_16x16x32_bf16 v[24:27], v[136:139], v[178:181], v[24:27]
	v_mfma_f32_16x16x32_bf16 v[12:15], v[128:131], v[186:189], v[12:15]
	v_mfma_f32_16x16x32_bf16 v[8:11], v[136:139], v[186:189], v[8:11]
	v_mfma_f32_16x16x32_bf16 v[60:63], v[132:135], v[164:167], v[60:63]
	v_mfma_f32_16x16x32_bf16 v[56:59], v[140:143], v[164:167], v[56:59]
	v_mfma_f32_16x16x32_bf16 v[44:47], v[132:135], v[174:177], v[44:47]
	v_mfma_f32_16x16x32_bf16 v[40:43], v[140:143], v[174:177], v[40:43]
	v_mfma_f32_16x16x32_bf16 v[28:31], v[132:135], v[182:185], v[28:31]
	v_mfma_f32_16x16x32_bf16 v[24:27], v[140:143], v[182:185], v[24:27]
	v_mfma_f32_16x16x32_bf16 v[12:15], v[132:135], v[190:193], v[12:15]
	v_mfma_f32_16x16x32_bf16 v[8:11], v[140:143], v[190:193], v[8:11]
	s_setprio 0
	s_setprio 1
	v_mfma_f32_16x16x32_bf16 v[52:55], v[144:147], v[160:163], v[52:55]
	v_mfma_f32_16x16x32_bf16 v[48:51], v[152:155], v[160:163], v[48:51]
	v_mfma_f32_16x16x32_bf16 v[36:39], v[144:147], v[168:171], v[36:39]
	v_mfma_f32_16x16x32_bf16 v[32:35], v[152:155], v[168:171], v[32:35]
	v_mfma_f32_16x16x32_bf16 v[20:23], v[144:147], v[178:181], v[20:23]
	v_mfma_f32_16x16x32_bf16 v[16:19], v[152:155], v[178:181], v[16:19]
	v_mfma_f32_16x16x32_bf16 v[4:7], v[144:147], v[186:189], v[4:7]
	v_mfma_f32_16x16x32_bf16 v[0:3], v[152:155], v[186:189], v[0:3]
	v_mfma_f32_16x16x32_bf16 v[52:55], v[148:151], v[164:167], v[52:55]
	v_mfma_f32_16x16x32_bf16 v[48:51], v[156:159], v[164:167], v[48:51]
	v_mfma_f32_16x16x32_bf16 v[36:39], v[148:151], v[174:177], v[36:39]
	v_mfma_f32_16x16x32_bf16 v[32:35], v[156:159], v[174:177], v[32:35]
	v_mfma_f32_16x16x32_bf16 v[20:23], v[148:151], v[182:185], v[20:23]
	v_mfma_f32_16x16x32_bf16 v[16:19], v[156:159], v[182:185], v[16:19]
	v_mfma_f32_16x16x32_bf16 v[4:7], v[148:151], v[190:193], v[4:7]
	v_mfma_f32_16x16x32_bf16 v[0:3], v[156:159], v[190:193], v[0:3]
	s_setprio 0
	s_barrier
; #define PG8_STAGE(bufoff, gbase, voff) do { _Pragma("unroll") for (int _i = 0; _i < 2; ++_i) \
;         { unsigned vo_ = (voff) + _i * voff##_d; asm volatile("" : "+v"(vo_)); __builtin_amdgcn_global_load_lds((const unsigned*)((const char*)(gbase) + vo_), (PG8_LAS unsigned*)(lds + (bufoff) + ldsw + _i * 8192), 16, 0, 0); } } while (0)
; #define PG8_LDA(dst, b, h) do { _Pragma("unroll") for (int m = 0; m < 4; ++m) _Pragma("unroll") for (int k = 0; k < 2; ++k) dst[m][k] = *(const PG8_LAS bf16x8*)(lds + PG8_SA(b, h) + aoff + m * 2048 + k * 1024); } while (0)
; #define PG8_LDB(dst, b, h) do { _Pragma("unroll") for (int n = 0; n < 2; ++n) _Pragma("unroll") for (int k = 0; k < 2; ++k) dst[n][k] = *(const PG8_LAS bf16x8*)(lds + PG8_SB(b, h) + boff + n * 2048 + k * 1024); } while (0)
; #define PG8_WAIT_V(n) asm volatile("s_waitcnt vmcnt(" #n ")" ::: "memory")
; #define PG8_WAIT_L(n) asm volatile("s_waitcnt lgkmcnt(" #n ")" ::: "memory")
; #define PG8_BAR __builtin_amdgcn_s_barrier()
; #define PG8_SCHED __builtin_amdgcn_sched_barrier(0)
; template <class Epi, class Sched, bool ALIGN_EPI, bool F8 = false>
; __device__ __forceinline__ void gemm_phase(PG8_LAS unsigned char* lds, const Gemm g, const Sched& S, const Epi& E, const int wid) {
;     ...
;             PG8_LDB(B0, 1, 0); PG8_LDB(B1, 1, 1); PG8_SCHED; PG8_LDA(At, 1, 0); PG8_STAGE(PG8_SA(0, 1), a2 + hA, voffA);
;             PG8_WAIT_V(8); PG8_WAIT_L(0); PG8_BAR; PG8_MMA(0, 0, At, B0); PG8_MMA(0, 1, At, B1); PG8_BAR; PG8_SCHED;
	s_add_i32 s77, 0, 0x18000
	s_add_i32 s80, 0, 0x1c000
	v_add_u32_e32 v140, s77, v243
	v_add_u32_e32 v156, s80, v243
	ds_read_b128 v[128:131], v140
	ds_read_b128 v[132:135], v140 offset:1024
	ds_read_b128 v[136:139], v140 offset:2048
	ds_read_b128 v[140:143], v140 offset:3072
	ds_read_b128 v[144:147], v156
	ds_read_b128 v[148:151], v156 offset:1024
	ds_read_b128 v[152:155], v156 offset:2048
	ds_read_b128 v[156:159], v156 offset:3072
	s_add_u32 s78, s48, 0x80000
	s_mov_b32 m0, s62
	ds_read_b128 v[160:163], v244 offset:32768
	ds_read_b128 v[164:167], v244 offset:33792
	ds_read_b128 v[168:171], v244 offset:34816
	ds_read_b128 v[174:177], v244 offset:35840
	ds_read_b128 v[178:181], v244 offset:36864
	ds_read_b128 v[182:185], v244 offset:37888
	s_addc_u32 s79, s49, 0
	ds_read_b128 v[186:189], v244 offset:38912
	global_load_lds_dwordx4 v173, s[78:79]
	s_mov_b32 m0, s63
	ds_read_b128 v[190:193], v244 offset:39936
	global_load_lds_dwordx4 v242, s[78:79]
	s_waitcnt vmcnt(8)
	s_waitcnt lgkmcnt(0)
	s_barrier
	s_setprio 1
	s_waitcnt lgkmcnt(0)
	v_mfma_f32_16x16x32_bf16 v[124:127], v[128:131], v[160:163], v[124:127]
	v_mfma_f32_16x16x32_bf16 v[120:123], v[136:139], v[160:163], v[120:123]
	v_mfma_f32_16x16x32_bf16 v[108:111], v[128:131], v[168:171], v[108:111]
	v_mfma_f32_16x16x32_bf16 v[104:107], v[136:139], v[168:171], v[104:107]
	v_mfma_f32_16x16x32_bf16 v[92:95], v[128:131], v[178:181], v[92:95]
	v_mfma_f32_16x16x32_bf16 v[88:91], v[136:139], v[178:181], v[88:91]
	v_mfma_f32_16x16x32_bf16 v[76:79], v[128:131], v[186:189], v[76:79]
	v_mfma_f32_16x16x32_bf16 v[72:75], v[136:139], v[186:189], v[72:75]
	v_mfma_f32_16x16x32_bf16 v[124:127], v[132:135], v[164:167], v[124:127]
	v_mfma_f32_16x16x32_bf16 v[120:123], v[140:143], v[164:167], v[120:123]
	v_mfma_f32_16x16x32_bf16 v[108:111], v[132:135], v[174:177], v[108:111]
	v_mfma_f32_16x16x32_bf16 v[104:107], v[140:143], v[174:177], v[104:107]
	v_mfma_f32_16x16x32_bf16 v[92:95], v[132:135], v[182:185], v[92:95]
	v_mfma_f32_16x16x32_bf16 v[88:91], v[140:143], v[182:185], v[88:91]
	v_mfma_f32_16x16x32_bf16 v[76:79], v[132:135], v[190:193], v[76:79]
	v_mfma_f32_16x16x32_bf16 v[72:75], v[140:143], v[190:193], v[72:75]
	s_setprio 0
	s_setprio 1
	v_mfma_f32_16x16x32_bf16 v[116:119], v[144:147], v[160:163], v[116:119]
	v_mfma_f32_16x16x32_bf16 v[112:115], v[152:155], v[160:163], v[112:115]
	v_mfma_f32_16x16x32_bf16 v[100:103], v[144:147], v[168:171], v[100:103]
	v_mfma_f32_16x16x32_bf16 v[96:99], v[152:155], v[168:171], v[96:99]
	v_mfma_f32_16x16x32_bf16 v[84:87], v[144:147], v[178:181], v[84:87]
	v_mfma_f32_16x16x32_bf16 v[80:83], v[152:155], v[178:181], v[80:83]
	v_mfma_f32_16x16x32_bf16 v[68:71], v[144:147], v[186:189], v[68:71]
	v_mfma_f32_16x16x32_bf16 v[64:67], v[152:155], v[186:189], v[64:67]
	v_mfma_f32_16x16x32_bf16 v[116:119], v[148:151], v[164:167], v[116:119]
	v_mfma_f32_16x16x32_bf16 v[112:115], v[156:159], v[164:167], v[112:115]
	v_mfma_f32_16x16x32_bf16 v[100:103], v[148:151], v[174:177], v[100:103]
	v_mfma_f32_16x16x32_bf16 v[96:99], v[156:159], v[174:177], v[96:99]
	v_mfma_f32_16x16x32_bf16 v[84:87], v[148:151], v[182:185], v[84:87]
	v_mfma_f32_16x16x32_bf16 v[80:83], v[156:159], v[182:185], v[80:83]
	v_mfma_f32_16x16x32_bf16 v[68:71], v[148:151], v[190:193], v[68:71]
	v_mfma_f32_16x16x32_bf16 v[64:67], v[156:159], v[190:193], v[64:67]
	s_setprio 0
	s_barrier
; #define PG8_STAGE(bufoff, gbase, voff) do { _Pragma("unroll") for (int _i = 0; _i < 2; ++_i) \
;         { unsigned vo_ = (voff) + _i * voff##_d; asm volatile("" : "+v"(vo_)); __builtin_amdgcn_global_load_lds((const unsigned*)((const char*)(gbase) + vo_), (PG8_LAS unsigned*)(lds + (bufoff) + ldsw + _i * 8192), 16, 0, 0); } } while (0)
; #define PG8_LDA(dst, b, h) do { _Pragma("unroll") for (int m = 0; m < 4; ++m) _Pragma("unroll") for (int k = 0; k < 2; ++k) dst[m][k] = *(const PG8_LAS bf16x8*)(lds + PG8_SA(b, h) + aoff + m * 2048 + k * 1024); } while (0)
; #define PG8_WAIT_V(n) asm volatile("s_waitcnt vmcnt(" #n ")" ::: "memory")
; #define PG8_WAIT_L(n) asm volatile("s_waitcnt lgkmcnt(" #n ")" ::: "memory")
; #define PG8_BAR __builtin_amdgcn_s_barrier()
; #define PG8_SCHED __builtin_amdgcn_sched_barrier(0)
; template <class Epi, class Sched, bool ALIGN_EPI, bool F8 = false>
; __device__ __forceinline__ void gemm_phase(PG8_LAS unsigned char* lds, const Gemm g, const Sched& S, const Epi& E, const int wid) {
;     ...
;             PG8_LDA(At, 1, 1); PG8_STAGE(PG8_SB(1, 0), b3, voffB); PG8_STAGE(PG8_SB(1, 1), b3 + hB, voffB); PG8_STAGE(PG8_SA(1, 0), a3, voffA);
;             PG8_WAIT_V(8); PG8_WAIT_L(0); PG8_BAR; PG8_MMA(1, 0, At, B0); PG8_MMA(1, 1, At, B1); PG8_BAR; PG8_SCHED;
	ds_read_b128 v[160:163], v244 offset:49152
	ds_read_b128 v[164:167], v244 offset:50176
	ds_read_b128 v[168:171], v244 offset:51200
	ds_read_b128 v[174:177], v244 offset:52224
	ds_read_b128 v[178:181], v244 offset:53248
	s_add_i32 s77, s77, s58
	s_add_u32 s100, s50, s2
	s_addc_u32 s101, s51, s3
	s_mov_b32 m0, s77
	ds_read_b128 v[182:185], v244 offset:54272
	global_load_lds_dwordx4 v173, s[100:101]
	s_add_i32 m0, s77, 0x2000
	s_add_u32 s100, s50, s2
	s_addc_u32 s101, s51, s3
	s_add_u32 s50, s50, 0x80080
	global_load_lds_dwordx4 v242, s[100:101]
	s_addc_u32 s51, s51, 0
	s_add_i32 s77, s80, s58
	s_mov_b32 m0, s77
	ds_read_b128 v[186:189], v244 offset:55296
	global_load_lds_dwordx4 v173, s[50:51]
	s_add_i32 m0, s77, 0x2000
	ds_read_b128 v[190:193], v244 offset:56320
	global_load_lds_dwordx4 v242, s[50:51]
	s_mov_b32 m0, s67
	s_add_u32 s100, s48, s2
	s_addc_u32 s101, s49, s3
	global_load_lds_dwordx4 v173, s[100:101]
	s_mov_b32 m0, s68
	s_add_u32 s100, s48, s2
	s_addc_u32 s101, s49, s3
	global_load_lds_dwordx4 v242, s[100:101]
	s_waitcnt vmcnt(8)
	s_waitcnt lgkmcnt(0)
	s_barrier
	s_setprio 1
	s_waitcnt lgkmcnt(0)
	v_mfma_f32_16x16x32_bf16 v[60:63], v[128:131], v[160:163], v[60:63]
	v_mfma_f32_16x16x32_bf16 v[56:59], v[136:139], v[160:163], v[56:59]
	v_mfma_f32_16x16x32_bf16 v[44:47], v[128:131], v[168:171], v[44:47]
	v_mfma_f32_16x16x32_bf16 v[40:43], v[136:139], v[168:171], v[40:43]
	v_mfma_f32_16x16x32_bf16 v[28:31], v[128:131], v[178:181], v[28:31]
	v_mfma_f32_16x16x32_bf16 v[24:27], v[136:139], v[178:181], v[24:27]
	v_mfma_f32_16x16x32_bf16 v[12:15], v[128:131], v[186:189], v[12:15]
	v_mfma_f32_16x16x32_bf16 v[8:11], v[136:139], v[186:189], v[8:11]
	v_mfma_f32_16x16x32_bf16 v[60:63], v[132:135], v[164:167], v[60:63]
	v_mfma_f32_16x16x32_bf16 v[56:59], v[140:143], v[164:167], v[56:59]
	v_mfma_f32_16x16x32_bf16 v[44:47], v[132:135], v[174:177], v[44:47]
	v_mfma_f32_16x16x32_bf16 v[40:43], v[140:143], v[174:177], v[40:43]
	v_mfma_f32_16x16x32_bf16 v[28:31], v[132:135], v[182:185], v[28:31]
	v_mfma_f32_16x16x32_bf16 v[24:27], v[140:143], v[182:185], v[24:27]
	v_mfma_f32_16x16x32_bf16 v[12:15], v[132:135], v[190:193], v[12:15]
	v_mfma_f32_16x16x32_bf16 v[8:11], v[140:143], v[190:193], v[8:11]
	s_setprio 0
	s_setprio 1
	v_mfma_f32_16x16x32_bf16 v[52:55], v[144:147], v[160:163], v[52:55]
	v_mfma_f32_16x16x32_bf16 v[48:51], v[152:155], v[160:163], v[48:51]
	v_mfma_f32_16x16x32_bf16 v[36:39], v[144:147], v[168:171], v[36:39]
	v_mfma_f32_16x16x32_bf16 v[32:35], v[152:155], v[168:171], v[32:35]
	v_mfma_f32_16x16x32_bf16 v[20:23], v[144:147], v[178:181], v[20:23]
	v_mfma_f32_16x16x32_bf16 v[16:19], v[152:155], v[178:181], v[16:19]
	v_mfma_f32_16x16x32_bf16 v[4:7], v[144:147], v[186:189], v[4:7]
	v_mfma_f32_16x16x32_bf16 v[0:3], v[152:155], v[186:189], v[0:3]
	v_mfma_f32_16x16x32_bf16 v[52:55], v[148:151], v[164:167], v[52:55]
	v_mfma_f32_16x16x32_bf16 v[48:51], v[156:159], v[164:167], v[48:51]
	v_mfma_f32_16x16x32_bf16 v[36:39], v[148:151], v[174:177], v[36:39]
	v_mfma_f32_16x16x32_bf16 v[32:35], v[156:159], v[174:177], v[32:35]
	v_mfma_f32_16x16x32_bf16 v[20:23], v[148:151], v[182:185], v[20:23]
	v_mfma_f32_16x16x32_bf16 v[16:19], v[156:159], v[182:185], v[16:19]
	v_mfma_f32_16x16x32_bf16 v[4:7], v[148:151], v[190:193], v[4:7]
	v_mfma_f32_16x16x32_bf16 v[0:3], v[156:159], v[190:193], v[0:3]
	s_setprio 0
	s_barrier
	s_add_u32 s46, s46, 0x100
	s_addc_u32 s47, s47, 0
	s_add_u32 s74, s74, 0x100
	s_addc_u32 s75, s75, 0
	s_cmp_ge_i32 s76, s64
	s_mov_b32 s48, s76
	s_cbranch_scc0 .LBB0_1851
	s_mov_b32 s76, 0x28000
	s_mov_b32 s75, 0x30000
	s_mov_b32 s72, 0x80000
	s_mov_b32 s73, 0x90000
	s_mov_b32 s74, 0xa0000
	s_mov_b32 s77, 0x3f400000
	s_mov_b32 s78, 0x3fa00000
	s_mov_b32 s79, 0x3fe00000
	s_mov_b32 s80, 0x40600000

; #define PG8_STAGE(bufoff, gbase, voff) do { _Pragma("unroll") for (int _i = 0; _i < 2; ++_i) \
;         { unsigned vo_ = (voff) + _i * voff##_d; asm volatile("" : "+v"(vo_)); __builtin_amdgcn_global_load_lds((const unsigned*)((const char*)(gbase) + vo_), (PG8_LAS unsigned*)(lds + (bufoff) + ldsw + _i * 8192), 16, 0, 0); } } while (0)
; #define PG8_LDA(dst, b, h) do { _Pragma("unroll") for (int m = 0; m < 4; ++m) _Pragma("unroll") for (int k = 0; k < 2; ++k) dst[m][k] = *(const PG8_LAS bf16x8*)(lds + PG8_SA(b, h) + aoff + m * 2048 + k * 1024); } while (0)
; #define PG8_LDB(dst, b, h) do { _Pragma("unroll") for (int n = 0; n < 2; ++n) _Pragma("unroll") for (int k = 0; k < 2; ++k) dst[n][k] = *(const PG8_LAS bf16x8*)(lds + PG8_SB(b, h) + boff + n * 2048 + k * 1024); } while (0)
; #define PG8_WAIT_V(n) asm volatile("s_waitcnt vmcnt(" #n ")" ::: "memory")
; #define PG8_WAIT_L(n) asm volatile("s_waitcnt lgkmcnt(" #n ")" ::: "memory")
; #define PG8_BAR __builtin_amdgcn_s_barrier()
; #define PG8_SCHED __builtin_amdgcn_sched_barrier(0)
; template <class Epi, class Sched, bool ALIGN_EPI, bool F8 = false>
; __device__ __forceinline__ void gemm_phase(PG8_LAS unsigned char* lds, const Gemm g, const Sched& S, const Epi& E, const int wid) {
;     ...
;             PG8_LDB(B0, 0, 0); PG8_LDB(B1, 0, 1); PG8_SCHED; PG8_LDA(At, 0, 0); PG8_STAGE(PG8_SA(1, 1), a1 + hA, voffA);
;             PG8_WAIT_V(8); PG8_WAIT_L(0); PG8_BAR; PG8_MMA(0, 0, At, B0); PG8_MMA(0, 1, At, B1); PG8_BAR; PG8_SCHED;
;             PG8_LDA(At, 0, 1); PG8_STAGE(PG8_SB(0, 0), b2, voffB); PG8_STAGE(PG8_SB(0, 1), b2 + hB, voffB); PG8_STAGE(PG8_SA(0, 0), a2, voffA);
;             PG8_WAIT_V(8); PG8_WAIT_L(0); PG8_BAR; PG8_MMA(1, 0, At, B0); PG8_MMA(1, 1, At, B1); PG8_BAR; PG8_SCHED;
.LBB0_1990:
	s_add_i32 s66, s28, 2
	s_add_u32 s30, s26, 0xfff80080
	s_addc_u32 s29, s27, -1
	s_add_i32 s67, 0, 0x10000
	s_cmp_eq_u32 s58, s28
	s_cselect_b32 s29, s15, s29
	s_cselect_b32 s28, s17, s30
	v_add_u32_e32 v135, s67, v133
	s_cselect_b32 s31, s62, s65
	s_cselect_b32 s30, s63, s64
	s_add_i32 s70, 0, 0x14000
	ds_read_b128 v[136:139], v135
	ds_read_b128 v[140:143], v135 offset:1024
	ds_read_b128 v[144:147], v135 offset:2048
	ds_read_b128 v[148:151], v135 offset:3072
	v_add_u32_e32 v135, s70, v133
	ds_read_b128 v[152:155], v135
	ds_read_b128 v[156:159], v135 offset:1024
	ds_read_b128 v[160:163], v135 offset:2048
	ds_read_b128 v[164:167], v135 offset:3072
	ds_read_b128 v[168:171], v134
	ds_read_b128 v[172:175], v134 offset:1024
	ds_read_b128 v[176:179], v134 offset:2048
	ds_read_b128 v[180:183], v134 offset:3072
	ds_read_b128 v[184:187], v134 offset:4096
	ds_read_b128 v[188:191], v134 offset:5120
	s_add_i32 m0, s13, 0xc000
	ds_read_b128 v[192:195], v134 offset:6144
	global_load_lds_dwordx4 v129, s[26:27]
	s_add_i32 m0, s13, 0xe000
	ds_read_b128 v[196:199], v134 offset:7168
	global_load_lds_dwordx4 v132, s[26:27]
	s_waitcnt vmcnt(8)
	s_waitcnt lgkmcnt(0)
	s_barrier
	s_setprio 1
	s_waitcnt lgkmcnt(0)
	v_mfma_f32_16x16x32_bf16 v[120:123], v[136:139], v[168:171], v[120:123]
	v_mfma_f32_16x16x32_bf16 v[124:127], v[144:147], v[168:171], v[124:127]
	v_mfma_f32_16x16x32_bf16 v[108:111], v[136:139], v[176:179], v[108:111]
	v_mfma_f32_16x16x32_bf16 v[104:107], v[144:147], v[176:179], v[104:107]
	v_mfma_f32_16x16x32_bf16 v[92:95], v[136:139], v[184:187], v[92:95]
	v_mfma_f32_16x16x32_bf16 v[88:91], v[144:147], v[184:187], v[88:91]
	v_mfma_f32_16x16x32_bf16 v[76:79], v[136:139], v[192:195], v[76:79]
	v_mfma_f32_16x16x32_bf16 v[72:75], v[144:147], v[192:195], v[72:75]
	v_mfma_f32_16x16x32_bf16 v[120:123], v[140:143], v[172:175], v[120:123]
	v_mfma_f32_16x16x32_bf16 v[124:127], v[148:151], v[172:175], v[124:127]
	v_mfma_f32_16x16x32_bf16 v[108:111], v[140:143], v[180:183], v[108:111]
	v_mfma_f32_16x16x32_bf16 v[104:107], v[148:151], v[180:183], v[104:107]
	v_mfma_f32_16x16x32_bf16 v[92:95], v[140:143], v[188:191], v[92:95]
	v_mfma_f32_16x16x32_bf16 v[88:91], v[148:151], v[188:191], v[88:91]
	v_mfma_f32_16x16x32_bf16 v[76:79], v[140:143], v[196:199], v[76:79]
	v_mfma_f32_16x16x32_bf16 v[72:75], v[148:151], v[196:199], v[72:75]
	s_setprio 0
	s_setprio 1
	v_mfma_f32_16x16x32_bf16 v[116:119], v[152:155], v[168:171], v[116:119]
	v_mfma_f32_16x16x32_bf16 v[112:115], v[160:163], v[168:171], v[112:115]
	v_mfma_f32_16x16x32_bf16 v[100:103], v[152:155], v[176:179], v[100:103]
	v_mfma_f32_16x16x32_bf16 v[96:99], v[160:163], v[176:179], v[96:99]
	v_mfma_f32_16x16x32_bf16 v[84:87], v[152:155], v[184:187], v[84:87]
	v_mfma_f32_16x16x32_bf16 v[80:83], v[160:163], v[184:187], v[80:83]
	v_mfma_f32_16x16x32_bf16 v[60:63], v[152:155], v[192:195], v[60:63]
	v_mfma_f32_16x16x32_bf16 v[56:59], v[160:163], v[192:195], v[56:59]
	v_mfma_f32_16x16x32_bf16 v[116:119], v[156:159], v[172:175], v[116:119]
	v_mfma_f32_16x16x32_bf16 v[112:115], v[164:167], v[172:175], v[112:115]
	v_mfma_f32_16x16x32_bf16 v[100:103], v[156:159], v[180:183], v[100:103]
	v_mfma_f32_16x16x32_bf16 v[96:99], v[164:167], v[180:183], v[96:99]
	v_mfma_f32_16x16x32_bf16 v[84:87], v[156:159], v[188:191], v[84:87]
	v_mfma_f32_16x16x32_bf16 v[80:83], v[164:167], v[188:191], v[80:83]
	v_mfma_f32_16x16x32_bf16 v[60:63], v[156:159], v[196:199], v[60:63]
	v_mfma_f32_16x16x32_bf16 v[56:59], v[164:167], v[196:199], v[56:59]
	s_setprio 0
	s_barrier
	s_add_i32 s67, s67, s47
	ds_read_b128 v[168:171], v134 offset:16384
	ds_read_b128 v[172:175], v134 offset:17408
	ds_read_b128 v[176:179], v134 offset:18432
	s_mov_b32 m0, s67
	ds_read_b128 v[180:183], v134 offset:19456
	global_load_lds_dwordx4 v130, s[30:31]
	s_add_i32 m0, s67, 0x2000
	s_add_u32 s68, s30, 0x80000
	global_load_lds_dwordx4 v131, s[30:31]
	s_addc_u32 s69, s31, 0
	s_add_i32 s67, s70, s47
	s_mov_b32 m0, s67
	ds_read_b128 v[184:187], v134 offset:20480
	global_load_lds_dwordx4 v130, s[68:69]
	s_add_i32 m0, s67, 0x2000
	ds_read_b128 v[188:191], v134 offset:21504
	global_load_lds_dwordx4 v131, s[68:69]
	s_mov_b32 m0, s13
	ds_read_b128 v[192:195], v134 offset:22528
	global_load_lds_dwordx4 v129, s[28:29]
	s_mov_b32 m0, s49
	ds_read_b128 v[196:199], v134 offset:23552
	global_load_lds_dwordx4 v132, s[28:29]
	s_waitcnt vmcnt(8)
	s_waitcnt lgkmcnt(0)
	s_barrier
	s_setprio 1
	s_waitcnt lgkmcnt(0)
	v_mfma_f32_16x16x32_bf16 v[68:71], v[136:139], v[168:171], v[68:71]
	v_mfma_f32_16x16x32_bf16 v[64:67], v[144:147], v[168:171], v[64:67]
	v_mfma_f32_16x16x32_bf16 v[44:47], v[136:139], v[176:179], v[44:47]
	v_mfma_f32_16x16x32_bf16 v[40:43], v[144:147], v[176:179], v[40:43]
	v_mfma_f32_16x16x32_bf16 v[28:31], v[136:139], v[184:187], v[28:31]
	v_mfma_f32_16x16x32_bf16 v[24:27], v[144:147], v[184:187], v[24:27]
	v_mfma_f32_16x16x32_bf16 v[12:15], v[136:139], v[192:195], v[12:15]
	v_mfma_f32_16x16x32_bf16 v[8:11], v[144:147], v[192:195], v[8:11]
	v_mfma_f32_16x16x32_bf16 v[68:71], v[140:143], v[172:175], v[68:71]
	v_mfma_f32_16x16x32_bf16 v[64:67], v[148:151], v[172:175], v[64:67]
	v_mfma_f32_16x16x32_bf16 v[44:47], v[140:143], v[180:183], v[44:47]
	v_mfma_f32_16x16x32_bf16 v[40:43], v[148:151], v[180:183], v[40:43]
	v_mfma_f32_16x16x32_bf16 v[28:31], v[140:143], v[188:191], v[28:31]
	v_mfma_f32_16x16x32_bf16 v[24:27], v[148:151], v[188:191], v[24:27]
	v_mfma_f32_16x16x32_bf16 v[12:15], v[140:143], v[196:199], v[12:15]
	v_mfma_f32_16x16x32_bf16 v[8:11], v[148:151], v[196:199], v[8:11]
	s_setprio 0
	s_setprio 1
	v_mfma_f32_16x16x32_bf16 v[52:55], v[152:155], v[168:171], v[52:55]
	v_mfma_f32_16x16x32_bf16 v[48:51], v[160:163], v[168:171], v[48:51]
	v_mfma_f32_16x16x32_bf16 v[36:39], v[152:155], v[176:179], v[36:39]
	v_mfma_f32_16x16x32_bf16 v[32:35], v[160:163], v[176:179], v[32:35]
	v_mfma_f32_16x16x32_bf16 v[20:23], v[152:155], v[184:187], v[20:23]
	v_mfma_f32_16x16x32_bf16 v[16:19], v[160:163], v[184:187], v[16:19]
	v_mfma_f32_16x16x32_bf16 v[4:7], v[152:155], v[192:195], v[4:7]
	v_mfma_f32_16x16x32_bf16 v[0:3], v[160:163], v[192:195], v[0:3]
	v_mfma_f32_16x16x32_bf16 v[52:55], v[156:159], v[172:175], v[52:55]
	v_mfma_f32_16x16x32_bf16 v[48:51], v[164:167], v[172:175], v[48:51]
	v_mfma_f32_16x16x32_bf16 v[36:39], v[156:159], v[180:183], v[36:39]
	v_mfma_f32_16x16x32_bf16 v[32:35], v[164:167], v[180:183], v[32:35]
	v_mfma_f32_16x16x32_bf16 v[20:23], v[156:159], v[188:191], v[20:23]
	v_mfma_f32_16x16x32_bf16 v[16:19], v[164:167], v[188:191], v[16:19]
	v_mfma_f32_16x16x32_bf16 v[4:7], v[156:159], v[196:199], v[4:7]
	v_mfma_f32_16x16x32_bf16 v[0:3], v[164:167], v[196:199], v[0:3]
	s_setprio 0
	s_barrier
; #define PG8_STAGE(bufoff, gbase, voff) do { _Pragma("unroll") for (int _i = 0; _i < 2; ++_i) \
;         { unsigned vo_ = (voff) + _i * voff##_d; asm volatile("" : "+v"(vo_)); __builtin_amdgcn_global_load_lds((const unsigned*)((const char*)(gbase) + vo_), (PG8_LAS unsigned*)(lds + (bufoff) + ldsw + _i * 8192), 16, 0, 0); } } while (0)
; #define PG8_LDA(dst, b, h) do { _Pragma("unroll") for (int m = 0; m < 4; ++m) _Pragma("unroll") for (int k = 0; k < 2; ++k) dst[m][k] = *(const PG8_LAS bf16x8*)(lds + PG8_SA(b, h) + aoff + m * 2048 + k * 1024); } while (0)
; #define PG8_LDB(dst, b, h) do { _Pragma("unroll") for (int n = 0; n < 2; ++n) _Pragma("unroll") for (int k = 0; k < 2; ++k) dst[n][k] = *(const PG8_LAS bf16x8*)(lds + PG8_SB(b, h) + boff + n * 2048 + k * 1024); } while (0)
; #define PG8_WAIT_V(n) asm volatile("s_waitcnt vmcnt(" #n ")" ::: "memory")
; #define PG8_WAIT_L(n) asm volatile("s_waitcnt lgkmcnt(" #n ")" ::: "memory")
; #define PG8_BAR __builtin_amdgcn_s_barrier()
; #define PG8_SCHED __builtin_amdgcn_sched_barrier(0)
; template <class Epi, class Sched, bool ALIGN_EPI, bool F8 = false>
; __device__ __forceinline__ void gemm_phase(PG8_LAS unsigned char* lds, const Gemm g, const Sched& S, const Epi& E, const int wid) {
;     ...
;             PG8_LDB(B0, 1, 0); PG8_LDB(B1, 1, 1); PG8_SCHED; PG8_LDA(At, 1, 0); PG8_STAGE(PG8_SA(0, 1), a2 + hA, voffA);
;             PG8_WAIT_V(8); PG8_WAIT_L(0); PG8_BAR; PG8_MMA(0, 0, At, B0); PG8_MMA(0, 1, At, B1); PG8_BAR; PG8_SCHED;
;             PG8_LDA(At, 1, 1); PG8_STAGE(PG8_SB(1, 0), b3, voffB); PG8_STAGE(PG8_SB(1, 1), b3 + hB, voffB); PG8_STAGE(PG8_SA(1, 0), a3, voffA);
;             PG8_WAIT_V(8); PG8_WAIT_L(0); PG8_BAR; PG8_MMA(1, 0, At, B0); PG8_MMA(1, 1, At, B1); PG8_BAR; PG8_SCHED;
	s_add_i32 s67, 0, 0x18000
	v_add_u32_e32 v135, s67, v133
	s_add_i32 s70, 0, 0x1c000
	ds_read_b128 v[136:139], v135
	ds_read_b128 v[140:143], v135 offset:1024
	ds_read_b128 v[144:147], v135 offset:2048
	ds_read_b128 v[148:151], v135 offset:3072
	v_add_u32_e32 v135, s70, v133
	ds_read_b128 v[152:155], v135
	ds_read_b128 v[156:159], v135 offset:1024
	ds_read_b128 v[160:163], v135 offset:2048
	ds_read_b128 v[164:167], v135 offset:3072
	s_add_u32 s68, s28, 0x80000
	s_mov_b32 m0, s50
	ds_read_b128 v[168:171], v134 offset:32768
	ds_read_b128 v[172:175], v134 offset:33792
	ds_read_b128 v[176:179], v134 offset:34816
	ds_read_b128 v[180:183], v134 offset:35840
	ds_read_b128 v[184:187], v134 offset:36864
	ds_read_b128 v[188:191], v134 offset:37888
	s_addc_u32 s69, s29, 0
	ds_read_b128 v[192:195], v134 offset:38912
	global_load_lds_dwordx4 v129, s[68:69]
	s_mov_b32 m0, s51
	ds_read_b128 v[196:199], v134 offset:39936
	global_load_lds_dwordx4 v132, s[68:69]
	s_waitcnt vmcnt(8)
	s_waitcnt lgkmcnt(0)
	s_barrier
	s_setprio 1
	s_waitcnt lgkmcnt(0)
	v_mfma_f32_16x16x32_bf16 v[120:123], v[136:139], v[168:171], v[120:123]
	v_mfma_f32_16x16x32_bf16 v[124:127], v[144:147], v[168:171], v[124:127]
	v_mfma_f32_16x16x32_bf16 v[108:111], v[136:139], v[176:179], v[108:111]
	v_mfma_f32_16x16x32_bf16 v[104:107], v[144:147], v[176:179], v[104:107]
	v_mfma_f32_16x16x32_bf16 v[92:95], v[136:139], v[184:187], v[92:95]
	v_mfma_f32_16x16x32_bf16 v[88:91], v[144:147], v[184:187], v[88:91]
	v_mfma_f32_16x16x32_bf16 v[76:79], v[136:139], v[192:195], v[76:79]
	v_mfma_f32_16x16x32_bf16 v[72:75], v[144:147], v[192:195], v[72:75]
	v_mfma_f32_16x16x32_bf16 v[120:123], v[140:143], v[172:175], v[120:123]
	v_mfma_f32_16x16x32_bf16 v[124:127], v[148:151], v[172:175], v[124:127]
	v_mfma_f32_16x16x32_bf16 v[108:111], v[140:143], v[180:183], v[108:111]
	v_mfma_f32_16x16x32_bf16 v[104:107], v[148:151], v[180:183], v[104:107]
	v_mfma_f32_16x16x32_bf16 v[92:95], v[140:143], v[188:191], v[92:95]
	v_mfma_f32_16x16x32_bf16 v[88:91], v[148:151], v[188:191], v[88:91]
	v_mfma_f32_16x16x32_bf16 v[76:79], v[140:143], v[196:199], v[76:79]
	v_mfma_f32_16x16x32_bf16 v[72:75], v[148:151], v[196:199], v[72:75]
	s_setprio 0
	s_setprio 1
	v_mfma_f32_16x16x32_bf16 v[116:119], v[152:155], v[168:171], v[116:119]
	v_mfma_f32_16x16x32_bf16 v[112:115], v[160:163], v[168:171], v[112:115]
	v_mfma_f32_16x16x32_bf16 v[100:103], v[152:155], v[176:179], v[100:103]
	v_mfma_f32_16x16x32_bf16 v[96:99], v[160:163], v[176:179], v[96:99]
	v_mfma_f32_16x16x32_bf16 v[84:87], v[152:155], v[184:187], v[84:87]
	v_mfma_f32_16x16x32_bf16 v[80:83], v[160:163], v[184:187], v[80:83]
	v_mfma_f32_16x16x32_bf16 v[60:63], v[152:155], v[192:195], v[60:63]
	v_mfma_f32_16x16x32_bf16 v[56:59], v[160:163], v[192:195], v[56:59]
	v_mfma_f32_16x16x32_bf16 v[116:119], v[156:159], v[172:175], v[116:119]
	v_mfma_f32_16x16x32_bf16 v[112:115], v[164:167], v[172:175], v[112:115]
	v_mfma_f32_16x16x32_bf16 v[100:103], v[156:159], v[180:183], v[100:103]
	v_mfma_f32_16x16x32_bf16 v[96:99], v[164:167], v[180:183], v[96:99]
	v_mfma_f32_16x16x32_bf16 v[84:87], v[156:159], v[188:191], v[84:87]
	v_mfma_f32_16x16x32_bf16 v[80:83], v[164:167], v[188:191], v[80:83]
	v_mfma_f32_16x16x32_bf16 v[60:63], v[156:159], v[196:199], v[60:63]
	v_mfma_f32_16x16x32_bf16 v[56:59], v[164:167], v[196:199], v[56:59]
	s_setprio 0
	s_barrier
	ds_read_b128 v[168:171], v134 offset:49152
	ds_read_b128 v[172:175], v134 offset:50176
	ds_read_b128 v[176:179], v134 offset:51200
	ds_read_b128 v[180:183], v134 offset:52224
	ds_read_b128 v[184:187], v134 offset:53248
	s_add_i32 s67, s67, s47
	s_add_u32 s100, s30, s2
	s_addc_u32 s101, s31, s3
	s_mov_b32 m0, s67
	ds_read_b128 v[188:191], v134 offset:54272
	global_load_lds_dwordx4 v130, s[100:101]
	s_add_i32 m0, s67, 0x2000
	s_add_u32 s100, s30, s2
	s_addc_u32 s101, s31, s3
	s_add_u32 s30, s30, 0x80080
	s_addc_u32 s31, s31, 0
	s_add_i32 s67, s70, s47
	global_load_lds_dwordx4 v131, s[100:101]
	s_mov_b32 m0, s67
	ds_read_b128 v[192:195], v134 offset:55296
	global_load_lds_dwordx4 v130, s[30:31]
	s_add_i32 m0, s67, 0x2000
	ds_read_b128 v[196:199], v134 offset:56320
	global_load_lds_dwordx4 v131, s[30:31]
	s_mov_b32 m0, s56
	s_add_u32 s100, s28, s2
	s_addc_u32 s101, s29, s3
	global_load_lds_dwordx4 v129, s[100:101]
	s_mov_b32 m0, s57
	s_add_u32 s100, s28, s2
	s_addc_u32 s101, s29, s3
	global_load_lds_dwordx4 v132, s[100:101]
	s_waitcnt vmcnt(8)
	s_waitcnt lgkmcnt(0)
	s_barrier
	s_setprio 1
	s_waitcnt lgkmcnt(0)
	v_mfma_f32_16x16x32_bf16 v[68:71], v[136:139], v[168:171], v[68:71]
	v_mfma_f32_16x16x32_bf16 v[64:67], v[144:147], v[168:171], v[64:67]
	v_mfma_f32_16x16x32_bf16 v[44:47], v[136:139], v[176:179], v[44:47]
	v_mfma_f32_16x16x32_bf16 v[40:43], v[144:147], v[176:179], v[40:43]
	v_mfma_f32_16x16x32_bf16 v[28:31], v[136:139], v[184:187], v[28:31]
	v_mfma_f32_16x16x32_bf16 v[24:27], v[144:147], v[184:187], v[24:27]
	v_mfma_f32_16x16x32_bf16 v[12:15], v[136:139], v[192:195], v[12:15]
	v_mfma_f32_16x16x32_bf16 v[8:11], v[144:147], v[192:195], v[8:11]
	v_mfma_f32_16x16x32_bf16 v[68:71], v[140:143], v[172:175], v[68:71]
	v_mfma_f32_16x16x32_bf16 v[64:67], v[148:151], v[172:175], v[64:67]
	v_mfma_f32_16x16x32_bf16 v[44:47], v[140:143], v[180:183], v[44:47]
	v_mfma_f32_16x16x32_bf16 v[40:43], v[148:151], v[180:183], v[40:43]
	v_mfma_f32_16x16x32_bf16 v[28:31], v[140:143], v[188:191], v[28:31]
	v_mfma_f32_16x16x32_bf16 v[24:27], v[148:151], v[188:191], v[24:27]
	v_mfma_f32_16x16x32_bf16 v[12:15], v[140:143], v[196:199], v[12:15]
	v_mfma_f32_16x16x32_bf16 v[8:11], v[148:151], v[196:199], v[8:11]
	s_setprio 0
	s_setprio 1
	v_mfma_f32_16x16x32_bf16 v[52:55], v[152:155], v[168:171], v[52:55]
	v_mfma_f32_16x16x32_bf16 v[48:51], v[160:163], v[168:171], v[48:51]
	v_mfma_f32_16x16x32_bf16 v[36:39], v[152:155], v[176:179], v[36:39]
	v_mfma_f32_16x16x32_bf16 v[32:35], v[160:163], v[176:179], v[32:35]
	v_mfma_f32_16x16x32_bf16 v[20:23], v[152:155], v[184:187], v[20:23]
	v_mfma_f32_16x16x32_bf16 v[16:19], v[160:163], v[184:187], v[16:19]
	v_mfma_f32_16x16x32_bf16 v[4:7], v[152:155], v[192:195], v[4:7]
	v_mfma_f32_16x16x32_bf16 v[0:3], v[160:163], v[192:195], v[0:3]
	v_mfma_f32_16x16x32_bf16 v[52:55], v[156:159], v[172:175], v[52:55]
	v_mfma_f32_16x16x32_bf16 v[48:51], v[164:167], v[172:175], v[48:51]
	v_mfma_f32_16x16x32_bf16 v[36:39], v[156:159], v[180:183], v[36:39]
	v_mfma_f32_16x16x32_bf16 v[32:35], v[164:167], v[180:183], v[32:35]
	v_mfma_f32_16x16x32_bf16 v[20:23], v[156:159], v[188:191], v[20:23]
	v_mfma_f32_16x16x32_bf16 v[16:19], v[164:167], v[188:191], v[16:19]
	v_mfma_f32_16x16x32_bf16 v[4:7], v[156:159], v[196:199], v[4:7]
	v_mfma_f32_16x16x32_bf16 v[0:3], v[164:167], v[196:199], v[0:3]
	s_setprio 0
	s_barrier
	s_add_u32 s26, s26, 0x100
	s_addc_u32 s27, s27, 0
	s_add_u32 s64, s64, 0x100
	s_addc_u32 s65, s65, 0
	s_cmp_ge_i32 s66, s52
	s_mov_b32 s28, s66
	s_cbranch_scc0 .LBB0_1990
	v_mov_b32_e32 v198, v204
